# attention tiles: all 8 K-fragment LDS reads of QK^T issued up front with counted lgkmcnt waits; V-image address block hoisted to item dispatch
# speedup vs baseline: 1.0032x; 1.0032x over previous
.LBB0_230:
	v_and_b32_e32 v223, 0xff, v160
	v_lshrrev_b32_e32 v224, 2, v223
	v_and_b32_e32 v225, 3, v223
	v_lshrrev_b32_e32 v226, 1, v225
	v_bfe_u32 v227, v224, 1, 1
	v_xor_b32_e32 v226, v226, v227
	v_lshlrev_b32_e32 v226, 6, v226
	v_and_b32_e32 v225, 1, v225
	v_lshl_or_b32 v226, v225, 5, v226
	v_lshl_add_u32 v226, v224, 7, v226
	v_add_u32_e32 v223, s78, v226
	v_and_b32_e32 v226, 63, v160
	v_lshrrev_b32_e32 v224, 5, v226
	v_bfe_u32 v227, v226, 2, 2
	v_lshl_add_u32 v224, v224, 2, v227
	v_lshlrev_b32_e32 v224, 7, v224
	v_bfe_u32 v227, v226, 3, 1
	v_lshl_or_b32 v224, v227, 6, v224
	v_bfe_u32 v227, v226, 4, 1
	v_lshl_or_b32 v224, v227, 5, v224
	v_and_b32_e32 v227, 3, v226
	v_lshl_or_b32 v224, v227, 3, v224
	v_add_u32_e32 v224, s78, v224
	v_xor_b32_e32 v225, 64, v224
	s_cmpk_gt_i32 s4, 0x27f
	s_mov_b64 s[0:1], -1
	s_cbranch_scc1 .LBB0_229
	s_lshl_b32 s82, s4, 1
	s_add_i32 s82, s82, s77
	s_cmpk_gt_i32 s82, 0x7f
	s_cbranch_scc0 .LBB0_429
	s_cmpk_gt_u32 s82, 0x27f
	s_cbranch_scc0 .LBB0_411
	s_cmpk_gt_u32 s82, 0x2bf
	s_cbranch_scc0 .LBB0_338
	s_cmpk_gt_u32 s82, 0x2ff
	s_cbranch_scc0 .LBB0_248
	s_cmpk_gt_u32 s82, 0x3ff
	s_cbranch_scc0 .LBB0_241
	s_lshl_b32 s0, s82, 5
	s_add_i32 s0, s0, 0x7fff8000
	v_mov_b32 v0, 0
	s_and_b32 s6, s0, 0x7fffff00
	v_add_u32_sdwa v8, v0, v160 dst_sel:DWORD dst_unused:UNUSED_PAD src0_sel:DWORD src1_sel:BYTE_0
	v_readlane_b32 s0, v254, 59
	v_and_b32_e32 v9, 31, v8
	s_or_b32 s0, s0, s6
	v_or_b32_e32 v1, s0, v9
	s_lshl_b32 s0, s82, 4
	s_bfe_u32 s5, s82, 0x20001
	s_and_b32 s7, s0, 64
	v_readlane_b32 s0, v254, 60
	s_or_b32 s0, s5, s0
	s_ashr_i32 s1, s0, 31
	v_readlane_b32 s12, v254, 14
	v_ashrrev_i32_e32 v0, 1, v8
	s_lshl_b32 s4, s5, 6
	s_or_b32 s8, s7, 0xd80
	s_lshl_b64 s[0:1], s[0:1], 2
	v_readlane_b32 s20, v254, 22
	v_and_b32_e32 v0, 0xffffffe0, v0
	v_readlane_b32 s21, v254, 23
	s_add_u32 s0, s20, s0
	v_add_u32_e32 v96, v1, v0
	s_addc_u32 s1, s21, s1
	v_mov_b64_e32 v[0:1], s[62:63]
	v_bfe_u32 v98, v8, 5, 1
	global_load_dword v99, v129, s[0:1]
	v_mad_i64_i32 v[2:3], s[0:1], v96, s87, v[0:1]
	s_lshl_b32 s92, s5, 7
	v_lshl_add_u64 v[2:3], v[2:3], 0, s[92:93]
	v_lshlrev_b32_e32 v128, 4, v98
	v_lshl_add_u64 v[2:3], v[2:3], 0, v[128:129]
	s_mov_b64 s[0:1], 0x1900
	v_ashrrev_i32_e32 v11, 2, v8
	v_lshl_add_u64 v[4:5], v[2:3], 0, s[0:1]
	s_movk_i32 s0, 0x1000
	s_or_b32 s7, s7, 0xe00
	v_add_u32_e32 v13, s6, v11
	v_add_co_u32_e32 v2, vcc, s0, v2
	v_mad_i64_i32 v[0:1], s[0:1], v13, s87, v[0:1]
	s_lshl_b32 s92, s7, 1
	v_and_b32_e32 v12, 3, v8
	v_lshl_add_u64 v[6:7], v[0:1], 0, s[92:93]
	s_lshl_b32 s92, s8, 1
	v_lshlrev_b32_e32 v128, 5, v12
	v_lshl_add_u64 v[0:1], v[0:1], 0, s[92:93]
	v_lshl_add_u64 v[0:1], v[0:1], 0, v[128:129]
	v_addc_co_u32_e32 v3, vcc, 0, v3, vcc
	global_load_dwordx4 v[64:67], v[4:5], off offset:32
	global_load_dwordx4 v[68:71], v[4:5], off offset:64
	v_lshl_add_u64 v[6:7], v[6:7], 0, v[128:129]
	global_load_dwordx4 v[40:43], v[0:1], off offset:16
	global_load_dwordx4 v[44:47], v[0:1], off
	s_waitcnt lgkmcnt(0)
	global_load_dwordx4 v[32:35], v[6:7], off offset:16
	global_load_dwordx4 v[36:39], v[6:7], off
	global_load_dwordx4 v[72:75], v[2:3], off offset:2304
	global_load_dwordx4 v[76:79], v[4:5], off offset:96
	v_lshrrev_b32_e32 v1, 3, v8
	v_bfe_u32 v2, v8, 3, 3
	v_lshlrev_b32_e32 v4, 1, v12
	v_lshrrev_b32_e32 v10, 5, v8
	v_bitop3_b32 v1, v4, v1, 7 bitop3:0x78
	v_bitop3_b32 v2, v4, v2, 1 bitop3:0x36
	v_bfe_u32 v4, v8, 1, 3
	v_mul_u32_u24_e32 v8, 0x440, v12
	v_lshl_add_u32 v5, v9, 7, s78
	v_mul_u32_u24_e32 v7, 0x88, v9
	v_lshlrev_b32_e32 v8, 1, v8
	v_lshlrev_b32_e32 v9, 1, v11
	s_movk_i32 s0, 0xff82
	v_lshl_add_u32 v3, v11, 7, s78
	v_cmp_lt_i32_e32 vcc, v168, v167
	v_add3_u32 v101, s78, v8, v9
	v_mul_lo_u32 v9, v11, s0
	v_cndmask_b32_e32 v6, v165, v168, vcc
	v_add3_u32 v102, v3, v9, v8
	v_bitop3_b32 v8, v10, v4, 1 bitop3:0x6c
	v_bitop3_b32 v9, v98, v4, 2 bitop3:0x36
	v_bitop3_b32 v10, v98, v4, 4 bitop3:0x36
	v_bitop3_b32 v4, v98, v4, 6 bitop3:0x36
	v_lshlrev_b32_e32 v0, 4, v12
	v_lshlrev_b32_e32 v1, 4, v1
	v_lshlrev_b32_e32 v2, 4, v2
	v_lshlrev_b32_e32 v100, 2, v6
	v_lshl_add_u32 v6, v98, 3, s78
	v_lshlrev_b32_e32 v8, 4, v8
	v_lshlrev_b32_e32 v9, 4, v9
	v_lshlrev_b32_e32 v10, 4, v10
	v_lshlrev_b32_e32 v4, 4, v4
	v_mov_b32_e32 v105, 0
	v_ashrrev_i32_e32 v97, 31, v96
	s_mov_b32 s5, 0
	v_add_u32_e32 v103, 64, v13
	v_mov_b32_e32 v112, 0xf149f2ca
	s_lshl_b32 s92, s7, 1
	v_lshlrev_b32_e32 v128, 1, v0
	s_lshl_b32 s0, s8, 1
	v_add_u32_e32 v104, v3, v1
	v_add_u32_e32 v106, v3, v2
	v_add_u32_e32 v107, v5, v8
	v_add_u32_e32 v108, v5, v9
	v_add_u32_e32 v109, v5, v10
	v_add_u32_e32 v110, v5, v4
	v_add_u32_e32 v111, v6, v7
	v_mov_b32_e32 v16, 0
	v_mov_b32_e32 v17, v105
	v_mov_b32_e32 v18, v105
	v_mov_b32_e32 v19, v105
	v_mov_b32_e32 v20, v105
	v_mov_b32_e32 v21, v105
	v_mov_b32_e32 v22, v105
	v_mov_b32_e32 v23, v105
	v_mov_b32_e32 v24, v105
	v_mov_b32_e32 v25, v105
	v_mov_b32_e32 v26, v105
	v_mov_b32_e32 v27, v105
	v_mov_b32_e32 v28, v105
	v_mov_b32_e32 v29, v105
	v_mov_b32_e32 v30, v105
	v_mov_b32_e32 v31, v105
	v_mov_b32_e32 v0, 0
	v_mov_b32_e32 v1, v105
	v_mov_b32_e32 v2, v105
	v_mov_b32_e32 v3, v105
	v_mov_b32_e32 v4, v105
	v_mov_b32_e32 v5, v105
	v_mov_b32_e32 v6, v105
	v_mov_b32_e32 v7, v105
	v_mov_b32_e32 v8, v105
	v_mov_b32_e32 v9, v105
	v_mov_b32_e32 v10, v105
	s_waitcnt vmcnt(0)
	v_mov_b64_e32 v[94:95], v[42:43]
	v_mov_b64_e32 v[90:91], v[46:47]
	v_mov_b64_e32 v[86:87], v[34:35]
	v_mov_b64_e32 v[82:83], v[38:39]
	v_mov_b32_e32 v11, v105
	v_mov_b32_e32 v12, v105
	v_mov_b32_e32 v13, v105
	v_mov_b32_e32 v14, v105
	v_mov_b32_e32 v15, v105
	v_mov_b64_e32 v[88:89], v[44:45]
	v_mov_b64_e32 v[92:93], v[40:41]
	v_mov_b64_e32 v[80:81], v[36:37]
	v_mov_b64_e32 v[84:85], v[32:33]
	v_readlane_b32 s13, v254, 15
	v_readlane_b32 s14, v254, 16
	v_readlane_b32 s15, v254, 17
	v_readlane_b32 s16, v254, 18
	v_readlane_b32 s17, v254, 19
	v_readlane_b32 s18, v254, 20
	v_readlane_b32 s19, v254, 21
	v_readlane_b32 s22, v254, 24
	v_readlane_b32 s23, v254, 25
	v_readlane_b32 s24, v254, 26
	v_readlane_b32 s25, v254, 27
	v_readlane_b32 s26, v254, 28
	v_readlane_b32 s27, v254, 29
	s_cmpk_eq_i32 s5, 0xc0
	s_cbranch_scc1 .LBB0_239
	s_branch .LBB0_238

.LBB0_239:
	s_barrier
	ds_write_b128 v104, v[44:47]
	ds_write_b128 v106, v[40:43]
	ds_write_b128 v223, v[36:39] offset:8192
	ds_write_b128 v223, v[32:35] offset:8208
	s_waitcnt lgkmcnt(0)
	s_barrier
	ds_read_b128 v[32:35], v107
	ds_read_b128 v[48:51], v107 offset:4096
	ds_read_b128 v[114:117], v108
	ds_read_b128 v[118:121], v108 offset:4096
	ds_read_b128 v[228:231], v109 offset:4096
	ds_read_b128 v[232:235], v110 offset:4096
	ds_read_b128 v[236:239], v109
	ds_read_b128 v[240:243], v110
	s_waitcnt lgkmcnt(7)
	v_mfma_f32_32x32x16_bf16 v[32:47], v[32:35], v[72:75], 0
	s_mov_b32 s6, 0x3e000000
	s_mov_b32 s1, 0xf149f2ca
	v_add_u32_e32 v135, 0x2000, v111
	s_add_i32 s5, s5, 64
	s_cmpk_lg_i32 s5, 0x100
	s_waitcnt lgkmcnt(6)
	v_mfma_f32_32x32x16_bf16 v[48:63], v[48:51], v[72:75], 0
	s_waitcnt lgkmcnt(5)
	v_mfma_f32_32x32x16_bf16 v[32:47], v[114:117], v[64:67], v[32:47]
	s_nop 0
	s_waitcnt lgkmcnt(4)
	v_mfma_f32_32x32x16_bf16 v[48:63], v[118:121], v[64:67], v[48:63]
	s_waitcnt lgkmcnt(3)
	v_mfma_f32_32x32x16_bf16 v[48:63], v[228:231], v[68:71], v[48:63]
	s_nop 0
	s_waitcnt lgkmcnt(2)
	v_mfma_f32_32x32x16_bf16 v[48:63], v[232:235], v[76:79], v[48:63]
	s_nop 0
	s_nop 0
	s_waitcnt lgkmcnt(1)
	v_mfma_f32_32x32x16_bf16 v[32:47], v[236:239], v[68:71], v[32:47]
	s_nop 7
	v_mul_f32_e64 v48, v48, s6
	v_mul_f32_e64 v49, v49, s6
	v_mul_f32_e64 v50, v50, s6
	v_mul_f32_e64 v51, v51, s6
	v_mul_f32_e64 v52, v52, s6
	v_mul_f32_e64 v53, v53, s6
	v_pk_mul_f32 v[54:55], v[54:55], s[6:7] op_sel_hi:[1,0]
	v_pk_mul_f32 v[56:57], v[56:57], s[6:7] op_sel_hi:[1,0]
	v_pk_mul_f32 v[58:59], v[58:59], s[6:7] op_sel_hi:[1,0]
	v_pk_mul_f32 v[60:61], v[60:61], s[6:7] op_sel_hi:[1,0]
	s_waitcnt lgkmcnt(0)
	v_mfma_f32_32x32x16_bf16 v[32:47], v[240:243], v[76:79], v[32:47]
	v_mul_f32_e64 v62, v62, s6
	v_mul_f32_e64 v63, v63, s6
	s_nop 9
	v_pk_mul_f32 v[114:115], v[32:33], s[6:7] op_sel_hi:[1,0]
	v_pk_mul_f32 v[34:35], v[34:35], s[6:7] op_sel_hi:[1,0]
	v_max3_f32 v32, v114, s1, v115
	v_pk_mul_f32 v[36:37], v[36:37], s[6:7] op_sel_hi:[1,0]
	v_max3_f32 v32, v32, v34, v35
	v_pk_mul_f32 v[38:39], v[38:39], s[6:7] op_sel_hi:[1,0]
	v_max3_f32 v32, v32, v36, v37
	v_pk_mul_f32 v[40:41], v[40:41], s[6:7] op_sel_hi:[1,0]
	v_max3_f32 v32, v32, v38, v39
	v_pk_mul_f32 v[42:43], v[42:43], s[6:7] op_sel_hi:[1,0]
	v_max3_f32 v32, v32, v40, v41
	v_pk_mul_f32 v[44:45], v[44:45], s[6:7] op_sel_hi:[1,0]
	v_max3_f32 v32, v32, v42, v43
	v_pk_mul_f32 v[46:47], v[46:47], s[6:7] op_sel_hi:[1,0]
	v_max3_f32 v32, v32, v44, v45
	v_max3_f32 v32, v32, v46, v47
	v_max3_f32 v32, v32, v48, v49
	v_max3_f32 v32, v32, v50, v51
	v_max3_f32 v32, v32, v52, v53
	v_max3_f32 v32, v32, v54, v55
	v_max3_f32 v32, v32, v56, v57
	v_max3_f32 v32, v32, v58, v59
	v_max3_f32 v32, v32, v60, v61
	v_max3_f32 v32, v32, v62, v63
	ds_bpermute_b32 v33, v100, v32
	v_cmp_lt_f32_e32 vcc, s86, v115
	s_waitcnt lgkmcnt(0)
	v_max3_f32 v33, v112, v32, v33
	v_sub_f32_e32 v113, v115, v33
	v_sub_f32_e32 v32, v112, v33
	v_sub_f32_e32 v112, v114, v33
	v_mul_f32_e32 v113, 0x3fb8aa3b, v113
	v_exp_f32_e32 v113, v113
	v_mul_f32_e32 v112, 0x3fb8aa3b, v112
	v_sub_f32_e32 v116, v35, v33
	v_exp_f32_e32 v112, v112
	v_sub_f32_e32 v115, v34, v33
	v_mul_f32_e32 v116, 0x3fb8aa3b, v116
	v_exp_f32_e32 v116, v116
	v_mul_f32_e32 v115, 0x3fb8aa3b, v115
	v_exp_f32_e32 v115, v115
	v_cndmask_b32_e32 v113, 0, v113, vcc
	v_cmp_lt_f32_e32 vcc, s86, v114
	v_mul_f32_e32 v32, 0x3fb8aa3b, v32
	v_exp_f32_e32 v32, v32
	v_cndmask_b32_e32 v112, 0, v112, vcc
	v_cmp_lt_f32_e32 vcc, s86, v35
	v_add_f32_e32 v114, 0, v112
	v_add_f32_e32 v114, v113, v114
	v_cndmask_b32_e32 v116, 0, v116, vcc
	v_cmp_lt_f32_e32 vcc, s86, v34
	v_sub_f32_e32 v35, v36, v33
	v_mul_f32_e32 v35, 0x3fb8aa3b, v35
	v_cndmask_b32_e32 v115, 0, v115, vcc
	v_add_f32_e32 v34, v115, v114
	v_sub_f32_e32 v114, v37, v33
	v_mul_f32_e32 v114, 0x3fb8aa3b, v114
	v_exp_f32_e32 v114, v114
	v_exp_f32_e32 v35, v35
	v_cmp_lt_f32_e32 vcc, s86, v37
	v_add_f32_e32 v34, v116, v34
	v_pk_mul_f32 v[30:31], v[30:31], v[32:33] op_sel_hi:[1,0]
	v_cndmask_b32_e32 v114, 0, v114, vcc
	v_cmp_lt_f32_e32 vcc, s86, v36
	v_sub_f32_e32 v36, v39, v33
	v_mul_f32_e32 v36, 0x3fb8aa3b, v36
	v_cndmask_b32_e32 v117, 0, v35, vcc
	v_sub_f32_e32 v35, v38, v33
	v_exp_f32_e32 v36, v36
	v_mul_f32_e32 v35, 0x3fb8aa3b, v35
	v_exp_f32_e32 v35, v35
	v_cmp_lt_f32_e32 vcc, s86, v39
	v_add_f32_e32 v34, v117, v34
	v_add_f32_e32 v34, v114, v34
	v_cndmask_b32_e32 v118, 0, v36, vcc
	v_cmp_lt_f32_e32 vcc, s86, v38
	v_sub_f32_e32 v36, v41, v33
	v_mul_f32_e32 v36, 0x3fb8aa3b, v36
	v_cndmask_b32_e32 v119, 0, v35, vcc
	v_sub_f32_e32 v35, v40, v33
	v_exp_f32_e32 v36, v36
	v_mul_f32_e32 v35, 0x3fb8aa3b, v35
	v_exp_f32_e32 v35, v35
	v_cmp_lt_f32_e32 vcc, s86, v41
	v_add_f32_e32 v34, v119, v34
	v_add_f32_e32 v34, v118, v34
	v_cndmask_b32_e32 v120, 0, v36, vcc
	v_cmp_lt_f32_e32 vcc, s86, v40
	v_sub_f32_e32 v36, v43, v33
	v_mul_f32_e32 v36, 0x3fb8aa3b, v36
	v_cndmask_b32_e32 v121, 0, v35, vcc
	v_sub_f32_e32 v35, v42, v33
	v_exp_f32_e32 v36, v36
	v_mul_f32_e32 v35, 0x3fb8aa3b, v35
	v_exp_f32_e32 v35, v35
	v_cmp_lt_f32_e32 vcc, s86, v43
	v_add_f32_e32 v34, v121, v34
	v_add_f32_e32 v34, v120, v34
	v_cndmask_b32_e32 v122, 0, v36, vcc
	v_cmp_lt_f32_e32 vcc, s86, v42
	v_sub_f32_e32 v36, v45, v33
	v_mul_f32_e32 v36, 0x3fb8aa3b, v36
	v_cndmask_b32_e32 v123, 0, v35, vcc
	v_sub_f32_e32 v35, v44, v33
	v_exp_f32_e32 v36, v36
	v_mul_f32_e32 v35, 0x3fb8aa3b, v35
	v_exp_f32_e32 v35, v35
	v_cmp_lt_f32_e32 vcc, s86, v45
	v_add_f32_e32 v34, v123, v34
	v_add_f32_e32 v34, v122, v34
	v_cndmask_b32_e32 v124, 0, v36, vcc
	v_cmp_lt_f32_e32 vcc, s86, v44
	v_sub_f32_e32 v36, v47, v33
	v_mul_f32_e32 v36, 0x3fb8aa3b, v36
	v_cndmask_b32_e32 v125, 0, v35, vcc
	v_sub_f32_e32 v35, v46, v33
	v_exp_f32_e32 v36, v36
	v_mul_f32_e32 v35, 0x3fb8aa3b, v35
	v_exp_f32_e32 v35, v35
	v_cmp_lt_f32_e32 vcc, s86, v47
	v_add_f32_e32 v34, v125, v34
	v_add_f32_e32 v34, v124, v34
	v_cndmask_b32_e32 v47, 0, v36, vcc
	v_cmp_lt_f32_e32 vcc, s86, v46
	v_sub_f32_e32 v36, v49, v33
	v_mul_f32_e32 v36, 0x3fb8aa3b, v36
	v_cndmask_b32_e32 v46, 0, v35, vcc
	v_sub_f32_e32 v35, v48, v33
	v_exp_f32_e32 v36, v36
	v_mul_f32_e32 v35, 0x3fb8aa3b, v35
	v_exp_f32_e32 v35, v35
	v_cmp_lt_f32_e32 vcc, s86, v49
	v_add_f32_e32 v34, v46, v34
	v_add_f32_e32 v34, v47, v34
	v_cndmask_b32_e32 v49, 0, v36, vcc
	v_cmp_lt_f32_e32 vcc, s86, v48
	v_sub_f32_e32 v36, v51, v33
	v_mul_f32_e32 v36, 0x3fb8aa3b, v36
	v_cndmask_b32_e32 v48, 0, v35, vcc
	v_sub_f32_e32 v35, v50, v33
	v_exp_f32_e32 v36, v36
	v_mul_f32_e32 v35, 0x3fb8aa3b, v35
	v_exp_f32_e32 v35, v35
	v_cmp_lt_f32_e32 vcc, s86, v51
	v_add_f32_e32 v34, v48, v34
	v_add_f32_e32 v34, v49, v34
	v_cndmask_b32_e32 v51, 0, v36, vcc
	v_cmp_lt_f32_e32 vcc, s86, v50
	v_sub_f32_e32 v36, v53, v33
	v_mul_f32_e32 v36, 0x3fb8aa3b, v36
	v_cndmask_b32_e32 v50, 0, v35, vcc
	v_sub_f32_e32 v35, v52, v33
	v_exp_f32_e32 v36, v36
	v_mul_f32_e32 v35, 0x3fb8aa3b, v35
	v_exp_f32_e32 v35, v35
	v_cmp_lt_f32_e32 vcc, s86, v53
	v_add_f32_e32 v34, v50, v34
	v_add_f32_e32 v34, v51, v34
	v_cndmask_b32_e32 v53, 0, v36, vcc
	v_cmp_lt_f32_e32 vcc, s86, v52
	v_sub_f32_e32 v36, v55, v33
	v_mul_f32_e32 v36, 0x3fb8aa3b, v36
	v_cndmask_b32_e32 v52, 0, v35, vcc
	v_sub_f32_e32 v35, v54, v33
	v_exp_f32_e32 v36, v36
	v_mul_f32_e32 v35, 0x3fb8aa3b, v35
	v_exp_f32_e32 v35, v35
	v_cmp_lt_f32_e32 vcc, s86, v55
	v_add_f32_e32 v34, v52, v34
	v_add_f32_e32 v34, v53, v34
	v_cndmask_b32_e32 v55, 0, v36, vcc
	v_cmp_lt_f32_e32 vcc, s86, v54
	v_sub_f32_e32 v36, v57, v33
	v_mul_f32_e32 v36, 0x3fb8aa3b, v36
	v_cndmask_b32_e32 v54, 0, v35, vcc
	v_sub_f32_e32 v35, v56, v33
	v_exp_f32_e32 v36, v36
	v_mul_f32_e32 v35, 0x3fb8aa3b, v35
	v_exp_f32_e32 v35, v35
	v_cmp_lt_f32_e32 vcc, s86, v57
	v_add_f32_e32 v34, v54, v34
	v_add_f32_e32 v34, v55, v34
	v_cndmask_b32_e32 v57, 0, v36, vcc
	v_cmp_lt_f32_e32 vcc, s86, v56
	v_sub_f32_e32 v36, v59, v33
	v_mul_f32_e32 v36, 0x3fb8aa3b, v36
	v_cndmask_b32_e32 v56, 0, v35, vcc
	v_sub_f32_e32 v35, v58, v33
	v_exp_f32_e32 v36, v36
	v_mul_f32_e32 v35, 0x3fb8aa3b, v35
	v_exp_f32_e32 v35, v35
	v_cmp_lt_f32_e32 vcc, s86, v59
	v_add_f32_e32 v34, v56, v34
	v_add_f32_e32 v34, v57, v34
	v_cndmask_b32_e32 v59, 0, v36, vcc
	v_cmp_lt_f32_e32 vcc, s86, v58
	v_cvt_pk_bf16_f32 v38, v112, v113
	v_add_u32_e32 v112, 0x3000, v111
	v_cndmask_b32_e32 v58, 0, v35, vcc
	v_add_f32_e32 v34, v58, v34
	v_add_f32_e32 v126, v59, v34
	v_sub_f32_e32 v34, v60, v33
	v_mul_f32_e32 v127, 0x3fb8aa3b, v34
	ds_read_b64_tr_b16 v[34:35], v224 offset:8192
	ds_read_b64_tr_b16 v[36:37], v224 offset:9216
	ds_read_b64_tr_b16 v[42:43], v225 offset:8192
	ds_read_b64_tr_b16 v[44:45], v225 offset:9216
	v_pk_mul_f32 v[28:29], v[28:29], v[32:33] op_sel_hi:[1,0]
	v_pk_mul_f32 v[26:27], v[26:27], v[32:33] op_sel_hi:[1,0]
	v_pk_mul_f32 v[24:25], v[24:25], v[32:33] op_sel_hi:[1,0]
	v_pk_mul_f32 v[22:23], v[22:23], v[32:33] op_sel_hi:[1,0]
	v_pk_mul_f32 v[20:21], v[20:21], v[32:33] op_sel_hi:[1,0]
	v_pk_mul_f32 v[18:19], v[18:19], v[32:33] op_sel_hi:[1,0]
	v_pk_mul_f32 v[16:17], v[16:17], v[32:33] op_sel_hi:[1,0]
	v_cvt_pk_bf16_f32 v39, v115, v116
	v_cvt_pk_bf16_f32 v40, v117, v114
	v_cvt_pk_bf16_f32 v41, v119, v118
	v_sub_f32_e32 v134, v61, v33
	v_pk_mul_f32 v[14:15], v[14:15], v[32:33] op_sel_hi:[1,0]
	s_waitcnt lgkmcnt(2)
	v_mfma_f32_32x32x16_bf16 v[16:31], v[34:37], v[38:41], v[16:31]
	ds_read_b64_tr_b16 v[34:35], v224 offset:10240
	ds_read_b64_tr_b16 v[36:37], v224 offset:11264
	v_mul_f32_e64 v12, v12, v32
	v_mul_f32_e64 v13, v13, v32
	v_mul_f32_e64 v10, v10, v32
	v_mul_f32_e64 v11, v11, v32
	v_pk_mul_f32 v[8:9], v[8:9], v[32:33] op_sel_hi:[1,0]
	v_pk_mul_f32 v[6:7], v[6:7], v[32:33] op_sel_hi:[1,0]
	v_pk_mul_f32 v[4:5], v[4:5], v[32:33] op_sel_hi:[1,0]
	v_pk_mul_f32 v[2:3], v[2:3], v[32:33] op_sel_hi:[1,0]
	v_pk_mul_f32 v[0:1], v[0:1], v[32:33] op_sel_hi:[1,0]
	v_cmp_lt_f32_e32 vcc, s86, v61
	v_sub_f32_e32 v61, v62, v33
	s_waitcnt lgkmcnt(2)
	v_mfma_f32_32x32x16_bf16 v[0:15], v[42:45], v[38:41], v[0:15]
	v_mul_f32_e32 v38, 0x3fb8aa3b, v134
	v_exp_f32_e32 v113, v38
	v_cvt_pk_bf16_f32 v38, v121, v120
	v_cvt_pk_bf16_f32 v39, v123, v122
	v_cvt_pk_bf16_f32 v40, v125, v124
	v_cvt_pk_bf16_f32 v41, v46, v47
	ds_read_b64_tr_b16 v[42:43], v225 offset:10240
	ds_read_b64_tr_b16 v[44:45], v225 offset:11264
	v_cndmask_b32_e32 v46, 0, v113, vcc
	s_waitcnt lgkmcnt(2)
	v_mfma_f32_32x32x16_bf16 v[16:31], v[34:37], v[38:41], v[16:31]
	v_exp_f32_e32 v34, v127
	v_cmp_lt_f32_e32 vcc, s86, v60
	s_nop 1
	v_cndmask_b32_e32 v47, 0, v34, vcc
	ds_read_b64_tr_b16 v[34:35], v224 offset:12288
	ds_read_b64_tr_b16 v[36:37], v224 offset:13312
	v_cmp_lt_f32_e32 vcc, s86, v63
	s_waitcnt lgkmcnt(2)
	v_mfma_f32_32x32x16_bf16 v[0:15], v[42:45], v[38:41], v[0:15]
	ds_read_b64_tr_b16 v[42:43], v225 offset:12288
	ds_read_b64_tr_b16 v[44:45], v225 offset:13312
	v_cvt_pk_bf16_f32 v38, v48, v49
	v_cvt_pk_bf16_f32 v39, v50, v51
	v_cvt_pk_bf16_f32 v40, v52, v53
	v_cvt_pk_bf16_f32 v41, v54, v55
	v_add_f32_e32 v60, v47, v126
	v_add_f32_e32 v60, v46, v60
	s_waitcnt lgkmcnt(2)
	v_mfma_f32_32x32x16_bf16 v[16:31], v[34:37], v[38:41], v[16:31]
	v_sub_f32_e32 v34, v63, v33
	v_mul_f32_e32 v34, 0x3fb8aa3b, v34
	v_exp_f32_e32 v34, v34
	v_mul_f32_e32 v35, 0x3fb8aa3b, v61
	v_exp_f32_e32 v48, v35
	v_cndmask_b32_e32 v49, 0, v34, vcc
	s_waitcnt lgkmcnt(0)
	v_mfma_f32_32x32x16_bf16 v[0:15], v[42:45], v[38:41], v[0:15]
	ds_read_b64_tr_b16 v[34:35], v224 offset:14336
	ds_read_b64_tr_b16 v[36:37], v224 offset:15360
	ds_read_b64_tr_b16 v[42:43], v225 offset:14336
	ds_read_b64_tr_b16 v[44:45], v225 offset:15360
	v_cmp_lt_f32_e32 vcc, s86, v62
	v_cvt_pk_bf16_f32 v38, v56, v57
	v_cvt_pk_bf16_f32 v39, v58, v59
	v_cndmask_b32_e32 v41, 0, v48, vcc
	v_add_f32_e32 v48, v41, v60
	v_cvt_pk_bf16_f32 v40, v47, v46
	v_cvt_pk_bf16_f32 v41, v41, v49
	s_waitcnt lgkmcnt(2)
	s_nop 0
	v_mfma_f32_32x32x16_bf16 v[16:31], v[34:37], v[38:41], v[16:31]
	v_add_f32_e32 v34, v49, v48
	ds_bpermute_b32 v35, v100, v34
	s_waitcnt lgkmcnt(0)
	v_add_f32_e32 v34, v34, v35
	v_mfma_f32_32x32x16_bf16 v[0:15], v[42:45], v[38:41], v[0:15]
	v_fmac_f32_e32 v34, v105, v32
	s_cbranch_scc1 .LBB0_237
	v_max_f32_e32 v32, v99, v99
	v_max_f32_e32 v35, v33, v33
	v_max_f32_e32 v32, v35, v32
	v_sub_f32_e32 v33, v33, v32
	v_sub_f32_e32 v32, v99, v32
	v_mul_f32_e32 v33, 0x3fb8aa3b, v33
	v_mul_f32_e32 v32, 0x3fb8aa3b, v32
	v_exp_f32_e32 v33, v33
	v_exp_f32_e32 v32, v32
	s_lshl_b32 s92, s4, 1
	v_lshlrev_b32_e32 v128, 3, v98
	v_fmac_f32_e32 v32, v33, v34
	v_div_scale_f32 v34, s[0:1], v32, v32, v33
	v_rcp_f32_e32 v35, v34
	v_readlane_b32 s0, v254, 43
	v_readlane_b32 s1, v254, 44
	v_fma_f32 v36, -v34, v35, 1.0
	v_fmac_f32_e32 v35, v36, v35
	v_div_scale_f32 v36, vcc, v33, v32, v33
	v_mul_f32_e32 v37, v36, v35
	v_fma_f32 v38, -v34, v37, v36
	v_fmac_f32_e32 v37, v38, v35
	v_fma_f32 v34, -v34, v37, v36
	v_div_fmas_f32 v34, v34, v35, v37
	v_div_fixup_f32 v32, v34, v32, v33
	v_lshlrev_b64 v[34:35], 11, v[96:97]
	v_lshl_add_u64 v[34:35], s[0:1], 0, v[34:35]
	v_lshl_add_u64 v[34:35], v[34:35], 0, s[92:93]
	v_pk_mul_f32 v[16:17], v[16:17], v[32:33] op_sel_hi:[1,0]
	v_pk_mul_f32 v[18:19], v[18:19], v[32:33] op_sel_hi:[1,0]
	v_cvt_pk_bf16_f32 v16, v16, v17
	v_cvt_pk_bf16_f32 v17, v18, v19
	v_lshl_add_u64 v[18:19], v[34:35], 0, v[128:129]
	s_mov_b64 s[0:1], 0x153ca600
	v_lshl_add_u64 v[34:35], v[18:19], 0, s[0:1]
	s_mov_b32 s0, 0x153ca000
	v_add_co_u32_e32 v18, vcc, s0, v18
	v_pk_mul_f32 v[0:1], v[0:1], v[32:33] op_sel_hi:[1,0]
	v_pk_mul_f32 v[2:3], v[2:3], v[32:33] op_sel_hi:[1,0]
	v_addc_co_u32_e32 v19, vcc, 0, v19, vcc
	v_cvt_pk_bf16_f32 v0, v0, v1
	v_cvt_pk_bf16_f32 v1, v2, v3
	global_store_dwordx2 v[18:19], v[16:17], off offset:1536
	v_pk_mul_f32 v[16:17], v[20:21], v[32:33] op_sel_hi:[1,0]
	v_pk_mul_f32 v[18:19], v[22:23], v[32:33] op_sel_hi:[1,0]
	global_store_dwordx2 v[34:35], v[0:1], off offset:64
	v_pk_mul_f32 v[0:1], v[4:5], v[32:33] op_sel_hi:[1,0]
	v_pk_mul_f32 v[2:3], v[6:7], v[32:33] op_sel_hi:[1,0]
	v_cvt_pk_bf16_f32 v16, v16, v17
	v_cvt_pk_bf16_f32 v17, v18, v19
	v_cvt_pk_bf16_f32 v0, v0, v1
	v_cvt_pk_bf16_f32 v1, v2, v3
	global_store_dwordx2 v[34:35], v[16:17], off offset:16
	v_pk_mul_f32 v[16:17], v[24:25], v[32:33] op_sel_hi:[1,0]
	v_pk_mul_f32 v[18:19], v[26:27], v[32:33] op_sel_hi:[1,0]
	global_store_dwordx2 v[34:35], v[0:1], off offset:80
	v_pk_mul_f32 v[0:1], v[8:9], v[32:33] op_sel_hi:[1,0]
	v_pk_mul_f32 v[2:3], v[10:11], v[32:33] op_sel_hi:[1,0]
	v_cvt_pk_bf16_f32 v16, v16, v17
	v_cvt_pk_bf16_f32 v17, v18, v19
	v_cvt_pk_bf16_f32 v0, v0, v1
	v_cvt_pk_bf16_f32 v1, v2, v3
	global_store_dwordx2 v[34:35], v[16:17], off offset:32
	v_pk_mul_f32 v[16:17], v[28:29], v[32:33] op_sel_hi:[1,0]
	v_pk_mul_f32 v[18:19], v[30:31], v[32:33] op_sel_hi:[1,0]
	global_store_dwordx2 v[34:35], v[0:1], off offset:96
	v_pk_mul_f32 v[0:1], v[12:13], v[32:33] op_sel_hi:[1,0]
	v_pk_mul_f32 v[2:3], v[14:15], v[32:33] op_sel_hi:[1,0]
	v_cvt_pk_bf16_f32 v16, v16, v17
	v_cvt_pk_bf16_f32 v17, v18, v19
	v_cvt_pk_bf16_f32 v0, v0, v1
	v_cvt_pk_bf16_f32 v1, v2, v3
	global_store_dwordx2 v[34:35], v[16:17], off offset:48
	global_store_dwordx2 v[34:35], v[0:1], off offset:112
	s_barrier
	s_mov_b64 s[0:1], 0

.LBB0_245:
	s_barrier
	ds_write_b128 v104, v[44:47]
	ds_write_b128 v105, v[40:43]
	ds_write_b128 v223, v[36:39] offset:8192
	ds_write_b128 v223, v[32:35] offset:8208
	s_waitcnt lgkmcnt(0)
	s_barrier
	ds_read_b128 v[32:35], v106
	ds_read_b128 v[48:51], v106 offset:4096
	ds_read_b128 v[114:117], v108
	ds_read_b128 v[118:121], v108 offset:4096
	ds_read_b128 v[228:231], v109 offset:4096
	ds_read_b128 v[232:235], v110 offset:4096
	ds_read_b128 v[236:239], v109
	ds_read_b128 v[240:243], v110
	s_waitcnt lgkmcnt(7)
	v_mfma_f32_32x32x16_bf16 v[32:47], v[32:35], v[64:67], 0
	s_mov_b32 s6, 0x3e000000
	s_mov_b32 s5, 0xf149f2ca
	v_add_u32_e32 v134, 0x2000, v111
	s_add_u32 s0, s0, 0x74000
	s_addc_u32 s1, s1, 0
	s_cmp_lg_u32 s0, 0x1d0000
	s_waitcnt lgkmcnt(6)
	v_mfma_f32_32x32x16_bf16 v[48:63], v[48:51], v[64:67], 0
	s_waitcnt lgkmcnt(5)
	v_mfma_f32_32x32x16_bf16 v[32:47], v[114:117], v[68:71], v[32:47]
	s_nop 0
	s_waitcnt lgkmcnt(4)
	v_mfma_f32_32x32x16_bf16 v[48:63], v[118:121], v[68:71], v[48:63]
	s_waitcnt lgkmcnt(3)
	v_mfma_f32_32x32x16_bf16 v[48:63], v[228:231], v[72:75], v[48:63]
	s_nop 0
	s_waitcnt lgkmcnt(2)
	v_mfma_f32_32x32x16_bf16 v[48:63], v[232:235], v[76:79], v[48:63]
	s_nop 0
	s_nop 0
	s_waitcnt lgkmcnt(1)
	v_mfma_f32_32x32x16_bf16 v[32:47], v[236:239], v[72:75], v[32:47]
	s_nop 7
	v_mul_f32_e64 v48, v48, s6
	v_mul_f32_e64 v49, v49, s6
	v_mul_f32_e64 v50, v50, s6
	v_mul_f32_e64 v51, v51, s6
	v_mul_f32_e64 v52, v52, s6
	v_mul_f32_e64 v53, v53, s6
	v_pk_mul_f32 v[54:55], v[54:55], s[6:7] op_sel_hi:[1,0]
	v_pk_mul_f32 v[56:57], v[56:57], s[6:7] op_sel_hi:[1,0]
	v_pk_mul_f32 v[58:59], v[58:59], s[6:7] op_sel_hi:[1,0]
	v_pk_mul_f32 v[60:61], v[60:61], s[6:7] op_sel_hi:[1,0]
	s_waitcnt lgkmcnt(0)
	v_mfma_f32_32x32x16_bf16 v[32:47], v[240:243], v[76:79], v[32:47]
	v_mul_f32_e64 v62, v62, s6
	v_mul_f32_e64 v63, v63, s6
	s_nop 9
	v_pk_mul_f32 v[114:115], v[32:33], s[6:7] op_sel_hi:[1,0]
	v_pk_mul_f32 v[34:35], v[34:35], s[6:7] op_sel_hi:[1,0]
	v_max3_f32 v32, v114, s5, v115
	v_pk_mul_f32 v[36:37], v[36:37], s[6:7] op_sel_hi:[1,0]
	v_max3_f32 v32, v32, v34, v35
	v_pk_mul_f32 v[38:39], v[38:39], s[6:7] op_sel_hi:[1,0]
	v_max3_f32 v32, v32, v36, v37
	v_pk_mul_f32 v[40:41], v[40:41], s[6:7] op_sel_hi:[1,0]
	v_max3_f32 v32, v32, v38, v39
	v_pk_mul_f32 v[42:43], v[42:43], s[6:7] op_sel_hi:[1,0]
	v_max3_f32 v32, v32, v40, v41
	v_pk_mul_f32 v[44:45], v[44:45], s[6:7] op_sel_hi:[1,0]
	v_max3_f32 v32, v32, v42, v43
	v_pk_mul_f32 v[46:47], v[46:47], s[6:7] op_sel_hi:[1,0]
	v_max3_f32 v32, v32, v44, v45
	v_max3_f32 v32, v32, v46, v47
	v_max3_f32 v32, v32, v48, v49
	v_max3_f32 v32, v32, v50, v51
	v_max3_f32 v32, v32, v52, v53
	v_max3_f32 v32, v32, v54, v55
	v_max3_f32 v32, v32, v56, v57
	v_max3_f32 v32, v32, v58, v59
	v_max3_f32 v32, v32, v60, v61
	v_max3_f32 v32, v32, v62, v63
	ds_bpermute_b32 v33, v101, v32
	v_cmp_lt_f32_e32 vcc, s86, v115
	s_waitcnt lgkmcnt(0)
	v_max3_f32 v33, v112, v32, v33
	v_sub_f32_e32 v113, v115, v33
	v_sub_f32_e32 v32, v112, v33
	v_sub_f32_e32 v112, v114, v33
	v_mul_f32_e32 v113, 0x3fb8aa3b, v113
	v_exp_f32_e32 v113, v113
	v_mul_f32_e32 v112, 0x3fb8aa3b, v112
	v_sub_f32_e32 v116, v35, v33
	v_exp_f32_e32 v112, v112
	v_sub_f32_e32 v115, v34, v33
	v_mul_f32_e32 v116, 0x3fb8aa3b, v116
	v_exp_f32_e32 v116, v116
	v_mul_f32_e32 v115, 0x3fb8aa3b, v115
	v_exp_f32_e32 v115, v115
	v_cndmask_b32_e32 v113, 0, v113, vcc
	v_cmp_lt_f32_e32 vcc, s86, v114
	v_mul_f32_e32 v32, 0x3fb8aa3b, v32
	v_exp_f32_e32 v32, v32
	v_cndmask_b32_e32 v112, 0, v112, vcc
	v_cmp_lt_f32_e32 vcc, s86, v35
	v_add_f32_e32 v114, 0, v112
	v_add_f32_e32 v114, v113, v114
	v_cndmask_b32_e32 v116, 0, v116, vcc
	v_cmp_lt_f32_e32 vcc, s86, v34
	v_sub_f32_e32 v35, v36, v33
	v_mul_f32_e32 v35, 0x3fb8aa3b, v35
	v_cndmask_b32_e32 v115, 0, v115, vcc
	v_add_f32_e32 v34, v115, v114
	v_sub_f32_e32 v114, v37, v33
	v_mul_f32_e32 v114, 0x3fb8aa3b, v114
	v_exp_f32_e32 v114, v114
	v_exp_f32_e32 v35, v35
	v_cmp_lt_f32_e32 vcc, s86, v37
	v_add_f32_e32 v34, v116, v34
	v_pk_mul_f32 v[30:31], v[30:31], v[32:33] op_sel_hi:[1,0]
	v_cndmask_b32_e32 v114, 0, v114, vcc
	v_cmp_lt_f32_e32 vcc, s86, v36
	v_sub_f32_e32 v36, v39, v33
	v_mul_f32_e32 v36, 0x3fb8aa3b, v36
	v_cndmask_b32_e32 v117, 0, v35, vcc
	v_sub_f32_e32 v35, v38, v33
	v_exp_f32_e32 v36, v36
	v_mul_f32_e32 v35, 0x3fb8aa3b, v35
	v_exp_f32_e32 v35, v35
	v_cmp_lt_f32_e32 vcc, s86, v39
	v_add_f32_e32 v34, v117, v34
	v_add_f32_e32 v34, v114, v34
	v_cndmask_b32_e32 v118, 0, v36, vcc
	v_cmp_lt_f32_e32 vcc, s86, v38
	v_sub_f32_e32 v36, v41, v33
	v_mul_f32_e32 v36, 0x3fb8aa3b, v36
	v_cndmask_b32_e32 v119, 0, v35, vcc
	v_sub_f32_e32 v35, v40, v33
	v_exp_f32_e32 v36, v36
	v_mul_f32_e32 v35, 0x3fb8aa3b, v35
	v_exp_f32_e32 v35, v35
	v_cmp_lt_f32_e32 vcc, s86, v41
	v_add_f32_e32 v34, v119, v34
	v_add_f32_e32 v34, v118, v34
	v_cndmask_b32_e32 v120, 0, v36, vcc
	v_cmp_lt_f32_e32 vcc, s86, v40
	v_sub_f32_e32 v36, v43, v33
	v_mul_f32_e32 v36, 0x3fb8aa3b, v36
	v_cndmask_b32_e32 v121, 0, v35, vcc
	v_sub_f32_e32 v35, v42, v33
	v_exp_f32_e32 v36, v36
	v_mul_f32_e32 v35, 0x3fb8aa3b, v35
	v_exp_f32_e32 v35, v35
	v_cmp_lt_f32_e32 vcc, s86, v43
	v_add_f32_e32 v34, v121, v34
	v_add_f32_e32 v34, v120, v34
	v_cndmask_b32_e32 v122, 0, v36, vcc
	v_cmp_lt_f32_e32 vcc, s86, v42
	v_sub_f32_e32 v36, v45, v33
	v_mul_f32_e32 v36, 0x3fb8aa3b, v36
	v_cndmask_b32_e32 v123, 0, v35, vcc
	v_sub_f32_e32 v35, v44, v33
	v_exp_f32_e32 v36, v36
	v_mul_f32_e32 v35, 0x3fb8aa3b, v35
	v_exp_f32_e32 v35, v35
	v_cmp_lt_f32_e32 vcc, s86, v45
	v_add_f32_e32 v34, v123, v34
	v_add_f32_e32 v34, v122, v34
	v_cndmask_b32_e32 v124, 0, v36, vcc
	v_cmp_lt_f32_e32 vcc, s86, v44
	v_sub_f32_e32 v36, v47, v33
	v_mul_f32_e32 v36, 0x3fb8aa3b, v36
	v_cndmask_b32_e32 v125, 0, v35, vcc
	v_sub_f32_e32 v35, v46, v33
	v_exp_f32_e32 v36, v36
	v_mul_f32_e32 v35, 0x3fb8aa3b, v35
	v_exp_f32_e32 v35, v35
	v_cmp_lt_f32_e32 vcc, s86, v47
	v_add_f32_e32 v34, v125, v34
	v_add_f32_e32 v34, v124, v34
	v_cndmask_b32_e32 v47, 0, v36, vcc
	v_cmp_lt_f32_e32 vcc, s86, v46
	v_sub_f32_e32 v36, v49, v33
	v_mul_f32_e32 v36, 0x3fb8aa3b, v36
	v_cndmask_b32_e32 v46, 0, v35, vcc
	v_sub_f32_e32 v35, v48, v33
	v_exp_f32_e32 v36, v36
	v_mul_f32_e32 v35, 0x3fb8aa3b, v35
	v_exp_f32_e32 v35, v35
	v_cmp_lt_f32_e32 vcc, s86, v49
	v_add_f32_e32 v34, v46, v34
	v_add_f32_e32 v34, v47, v34
	v_cndmask_b32_e32 v49, 0, v36, vcc
	v_cmp_lt_f32_e32 vcc, s86, v48
	v_sub_f32_e32 v36, v51, v33
	v_mul_f32_e32 v36, 0x3fb8aa3b, v36
	v_cndmask_b32_e32 v48, 0, v35, vcc
	v_sub_f32_e32 v35, v50, v33
	v_exp_f32_e32 v36, v36
	v_mul_f32_e32 v35, 0x3fb8aa3b, v35
	v_exp_f32_e32 v35, v35
	v_cmp_lt_f32_e32 vcc, s86, v51
	v_add_f32_e32 v34, v48, v34
	v_add_f32_e32 v34, v49, v34
	v_cndmask_b32_e32 v51, 0, v36, vcc
	v_cmp_lt_f32_e32 vcc, s86, v50
	v_sub_f32_e32 v36, v53, v33
	v_mul_f32_e32 v36, 0x3fb8aa3b, v36
	v_cndmask_b32_e32 v50, 0, v35, vcc
	v_sub_f32_e32 v35, v52, v33
	v_exp_f32_e32 v36, v36
	v_mul_f32_e32 v35, 0x3fb8aa3b, v35
	v_exp_f32_e32 v35, v35
	v_cmp_lt_f32_e32 vcc, s86, v53
	v_add_f32_e32 v34, v50, v34
	v_add_f32_e32 v34, v51, v34
	v_cndmask_b32_e32 v53, 0, v36, vcc
	v_cmp_lt_f32_e32 vcc, s86, v52
	v_sub_f32_e32 v36, v55, v33
	v_mul_f32_e32 v36, 0x3fb8aa3b, v36
	v_cndmask_b32_e32 v52, 0, v35, vcc
	v_sub_f32_e32 v35, v54, v33
	v_exp_f32_e32 v36, v36
	v_mul_f32_e32 v35, 0x3fb8aa3b, v35
	v_exp_f32_e32 v35, v35
	v_cmp_lt_f32_e32 vcc, s86, v55
	v_add_f32_e32 v34, v52, v34
	v_add_f32_e32 v34, v53, v34
	v_cndmask_b32_e32 v55, 0, v36, vcc
	v_cmp_lt_f32_e32 vcc, s86, v54
	v_sub_f32_e32 v36, v57, v33
	v_mul_f32_e32 v36, 0x3fb8aa3b, v36
	v_cndmask_b32_e32 v54, 0, v35, vcc
	v_sub_f32_e32 v35, v56, v33
	v_exp_f32_e32 v36, v36
	v_mul_f32_e32 v35, 0x3fb8aa3b, v35
	v_exp_f32_e32 v35, v35
	v_cmp_lt_f32_e32 vcc, s86, v57
	v_add_f32_e32 v34, v54, v34
	v_add_f32_e32 v34, v55, v34
	v_cndmask_b32_e32 v57, 0, v36, vcc
	v_cmp_lt_f32_e32 vcc, s86, v56
	v_sub_f32_e32 v36, v59, v33
	v_mul_f32_e32 v36, 0x3fb8aa3b, v36
	v_cndmask_b32_e32 v56, 0, v35, vcc
	v_sub_f32_e32 v35, v58, v33
	v_exp_f32_e32 v36, v36
	v_mul_f32_e32 v35, 0x3fb8aa3b, v35
	v_exp_f32_e32 v35, v35
	v_cmp_lt_f32_e32 vcc, s86, v59
	v_add_f32_e32 v34, v56, v34
	v_add_f32_e32 v34, v57, v34
	v_cndmask_b32_e32 v59, 0, v36, vcc
	v_cmp_lt_f32_e32 vcc, s86, v58
	v_cvt_pk_bf16_f32 v38, v112, v113
	v_add_u32_e32 v112, 0x3000, v111
	v_cndmask_b32_e32 v58, 0, v35, vcc
	v_add_f32_e32 v34, v58, v34
	v_add_f32_e32 v126, v59, v34
	v_sub_f32_e32 v34, v60, v33
	v_mul_f32_e32 v127, 0x3fb8aa3b, v34
	ds_read_b64_tr_b16 v[34:35], v224 offset:8192
	ds_read_b64_tr_b16 v[36:37], v224 offset:9216
	ds_read_b64_tr_b16 v[42:43], v225 offset:8192
	ds_read_b64_tr_b16 v[44:45], v225 offset:9216
	v_pk_mul_f32 v[28:29], v[28:29], v[32:33] op_sel_hi:[1,0]
	v_pk_mul_f32 v[26:27], v[26:27], v[32:33] op_sel_hi:[1,0]
	v_pk_mul_f32 v[24:25], v[24:25], v[32:33] op_sel_hi:[1,0]
	v_pk_mul_f32 v[22:23], v[22:23], v[32:33] op_sel_hi:[1,0]
	v_pk_mul_f32 v[20:21], v[20:21], v[32:33] op_sel_hi:[1,0]
	v_pk_mul_f32 v[18:19], v[18:19], v[32:33] op_sel_hi:[1,0]
	v_pk_mul_f32 v[16:17], v[16:17], v[32:33] op_sel_hi:[1,0]
	v_cvt_pk_bf16_f32 v39, v115, v116
	v_cvt_pk_bf16_f32 v40, v117, v114
	v_cvt_pk_bf16_f32 v41, v119, v118
	v_sub_f32_e32 v128, v61, v33
	v_pk_mul_f32 v[14:15], v[14:15], v[32:33] op_sel_hi:[1,0]
	s_waitcnt lgkmcnt(2)
	v_mfma_f32_32x32x16_bf16 v[16:31], v[34:37], v[38:41], v[16:31]
	ds_read_b64_tr_b16 v[34:35], v224 offset:10240
	ds_read_b64_tr_b16 v[36:37], v224 offset:11264
	v_mul_f32_e64 v12, v12, v32
	v_mul_f32_e64 v13, v13, v32
	v_mul_f32_e64 v10, v10, v32
	v_mul_f32_e64 v11, v11, v32
	v_pk_mul_f32 v[8:9], v[8:9], v[32:33] op_sel_hi:[1,0]
	v_pk_mul_f32 v[6:7], v[6:7], v[32:33] op_sel_hi:[1,0]
	v_pk_mul_f32 v[4:5], v[4:5], v[32:33] op_sel_hi:[1,0]
	v_pk_mul_f32 v[2:3], v[2:3], v[32:33] op_sel_hi:[1,0]
	v_pk_mul_f32 v[0:1], v[0:1], v[32:33] op_sel_hi:[1,0]
	v_cmp_lt_f32_e32 vcc, s86, v61
	v_sub_f32_e32 v61, v62, v33
	s_waitcnt lgkmcnt(2)
	v_mfma_f32_32x32x16_bf16 v[0:15], v[42:45], v[38:41], v[0:15]
	v_mul_f32_e32 v38, 0x3fb8aa3b, v128
	v_exp_f32_e32 v113, v38
	v_cvt_pk_bf16_f32 v38, v121, v120
	v_cvt_pk_bf16_f32 v39, v123, v122
	v_cvt_pk_bf16_f32 v40, v125, v124
	v_cvt_pk_bf16_f32 v41, v46, v47
	ds_read_b64_tr_b16 v[42:43], v225 offset:10240
	ds_read_b64_tr_b16 v[44:45], v225 offset:11264
	v_cndmask_b32_e32 v46, 0, v113, vcc
	s_waitcnt lgkmcnt(2)
	v_mfma_f32_32x32x16_bf16 v[16:31], v[34:37], v[38:41], v[16:31]
	v_exp_f32_e32 v34, v127
	v_cmp_lt_f32_e32 vcc, s86, v60
	s_nop 1
	v_cndmask_b32_e32 v47, 0, v34, vcc
	ds_read_b64_tr_b16 v[34:35], v224 offset:12288
	ds_read_b64_tr_b16 v[36:37], v224 offset:13312
	v_cmp_lt_f32_e32 vcc, s86, v63
	s_waitcnt lgkmcnt(2)
	v_mfma_f32_32x32x16_bf16 v[0:15], v[42:45], v[38:41], v[0:15]
	ds_read_b64_tr_b16 v[42:43], v225 offset:12288
	ds_read_b64_tr_b16 v[44:45], v225 offset:13312
	v_cvt_pk_bf16_f32 v38, v48, v49
	v_cvt_pk_bf16_f32 v39, v50, v51
	v_cvt_pk_bf16_f32 v40, v52, v53
	v_cvt_pk_bf16_f32 v41, v54, v55
	v_add_f32_e32 v60, v47, v126
	v_add_f32_e32 v60, v46, v60
	s_waitcnt lgkmcnt(2)
	v_mfma_f32_32x32x16_bf16 v[16:31], v[34:37], v[38:41], v[16:31]
	v_sub_f32_e32 v34, v63, v33
	v_mul_f32_e32 v34, 0x3fb8aa3b, v34
	v_exp_f32_e32 v34, v34
	v_mul_f32_e32 v35, 0x3fb8aa3b, v61
	v_exp_f32_e32 v48, v35
	v_cndmask_b32_e32 v49, 0, v34, vcc
	s_waitcnt lgkmcnt(0)
	v_mfma_f32_32x32x16_bf16 v[0:15], v[42:45], v[38:41], v[0:15]
	ds_read_b64_tr_b16 v[34:35], v224 offset:14336
	ds_read_b64_tr_b16 v[36:37], v224 offset:15360
	ds_read_b64_tr_b16 v[42:43], v225 offset:14336
	ds_read_b64_tr_b16 v[44:45], v225 offset:15360
	v_cmp_lt_f32_e32 vcc, s86, v62
	v_cvt_pk_bf16_f32 v38, v56, v57
	v_cvt_pk_bf16_f32 v39, v58, v59
	v_cndmask_b32_e32 v41, 0, v48, vcc
	v_add_f32_e32 v48, v41, v60
	v_cvt_pk_bf16_f32 v40, v47, v46
	v_cvt_pk_bf16_f32 v41, v41, v49
	s_waitcnt lgkmcnt(2)
	s_nop 0
	v_mfma_f32_32x32x16_bf16 v[16:31], v[34:37], v[38:41], v[16:31]
	v_add_f32_e32 v34, v49, v48
	ds_bpermute_b32 v35, v101, v34
	s_waitcnt lgkmcnt(0)
	v_add_f32_e32 v34, v34, v35
	v_mfma_f32_32x32x16_bf16 v[0:15], v[42:45], v[38:41], v[0:15]
	v_fmac_f32_e32 v34, v107, v32
	s_cbranch_scc1 .LBB0_243
	v_div_scale_f32 v32, s[0:1], v34, v34, 1.0
	v_rcp_f32_e32 v33, v32
	v_div_scale_f32 v35, vcc, 1.0, v34, 1.0
	v_readlane_b32 s0, v254, 43
	v_fma_f32 v36, -v32, v33, 1.0
	v_fmac_f32_e32 v33, v36, v33
	v_mul_f32_e32 v36, v35, v33
	v_fma_f32 v37, -v32, v36, v35
	v_fmac_f32_e32 v36, v37, v33
	v_fma_f32 v32, -v32, v36, v35
	v_div_fmas_f32 v32, v32, v33, v36
	v_div_fixup_f32 v32, v32, v34, 1.0
	v_lshlrev_b64 v[34:35], 11, v[96:97]
	v_readlane_b32 s1, v254, 44
	s_lshl_b32 s92, s4, 1
	v_pk_mul_f32 v[16:17], v[16:17], v[32:33] op_sel_hi:[1,0]
	v_lshl_add_u64 v[34:35], s[0:1], 0, v[34:35]
	v_lshl_add_u64 v[34:35], v[34:35], 0, s[92:93]
	v_pk_mul_f32 v[18:19], v[18:19], v[32:33] op_sel_hi:[1,0]
	v_lshlrev_b32_e32 v128, 3, v100
	v_cvt_pk_bf16_f32 v16, v16, v17
	v_cvt_pk_bf16_f32 v17, v18, v19
	v_lshl_add_u64 v[18:19], v[34:35], 0, v[128:129]
	s_mov_b64 s[0:1], 0x153ca200
	v_lshl_add_u64 v[34:35], v[18:19], 0, s[0:1]
	s_mov_b32 s0, 0x153ca000
	v_add_co_u32_e32 v18, vcc, s0, v18
	v_pk_mul_f32 v[0:1], v[0:1], v[32:33] op_sel_hi:[1,0]
	v_pk_mul_f32 v[2:3], v[2:3], v[32:33] op_sel_hi:[1,0]
	v_addc_co_u32_e32 v19, vcc, 0, v19, vcc
	v_cvt_pk_bf16_f32 v0, v0, v1
	v_cvt_pk_bf16_f32 v1, v2, v3
	global_store_dwordx2 v[18:19], v[16:17], off offset:512
	v_pk_mul_f32 v[16:17], v[20:21], v[32:33] op_sel_hi:[1,0]
	v_pk_mul_f32 v[18:19], v[22:23], v[32:33] op_sel_hi:[1,0]
	global_store_dwordx2 v[34:35], v[0:1], off offset:64
	v_pk_mul_f32 v[0:1], v[4:5], v[32:33] op_sel_hi:[1,0]
	v_pk_mul_f32 v[2:3], v[6:7], v[32:33] op_sel_hi:[1,0]
	v_cvt_pk_bf16_f32 v16, v16, v17
	v_cvt_pk_bf16_f32 v17, v18, v19
	v_cvt_pk_bf16_f32 v0, v0, v1
	v_cvt_pk_bf16_f32 v1, v2, v3
	global_store_dwordx2 v[34:35], v[16:17], off offset:16
	v_pk_mul_f32 v[16:17], v[24:25], v[32:33] op_sel_hi:[1,0]
	v_pk_mul_f32 v[18:19], v[26:27], v[32:33] op_sel_hi:[1,0]
	global_store_dwordx2 v[34:35], v[0:1], off offset:80
	v_pk_mul_f32 v[0:1], v[8:9], v[32:33] op_sel_hi:[1,0]
	v_pk_mul_f32 v[2:3], v[10:11], v[32:33] op_sel_hi:[1,0]
	v_cvt_pk_bf16_f32 v16, v16, v17
	v_cvt_pk_bf16_f32 v17, v18, v19
	v_cvt_pk_bf16_f32 v0, v0, v1
	v_cvt_pk_bf16_f32 v1, v2, v3
	global_store_dwordx2 v[34:35], v[16:17], off offset:32
	v_pk_mul_f32 v[16:17], v[28:29], v[32:33] op_sel_hi:[1,0]
	v_pk_mul_f32 v[18:19], v[30:31], v[32:33] op_sel_hi:[1,0]
	global_store_dwordx2 v[34:35], v[0:1], off offset:96
	v_pk_mul_f32 v[0:1], v[12:13], v[32:33] op_sel_hi:[1,0]
	v_pk_mul_f32 v[2:3], v[14:15], v[32:33] op_sel_hi:[1,0]
	v_cvt_pk_bf16_f32 v16, v16, v17
	v_cvt_pk_bf16_f32 v17, v18, v19
	v_cvt_pk_bf16_f32 v0, v0, v1
	v_cvt_pk_bf16_f32 v1, v2, v3
	global_store_dwordx2 v[34:35], v[16:17], off offset:48
	global_store_dwordx2 v[34:35], v[0:1], off offset:112
	s_barrier

.LBB0_270:
	s_barrier
	ds_write_b128 v126, v[32:35]
	ds_write_b128 v127, v[44:47]
	ds_write_b128 v223, v[40:43] offset:8192
	ds_write_b128 v223, v[36:39] offset:8208
	s_waitcnt lgkmcnt(0)
	s_barrier
	ds_read_b128 v[32:35], v138
	ds_read_b128 v[36:39], v138 offset:4096
	ds_read_b128 v[146:149], v139
	ds_read_b128 v[150:153], v139 offset:4096
	ds_read_b128 v[228:231], v140
	ds_read_b128 v[232:235], v140 offset:4096
	ds_read_b128 v[236:239], v141
	ds_read_b128 v[240:243], v141 offset:4096
	s_waitcnt lgkmcnt(7)
	v_mfma_f32_32x32x16_bf16 v[48:63], v[32:35], v[64:67], 0
	s_add_i32 s40, s33, s44
	v_cmp_ge_u32_e32 vcc, s40, v115
	v_cmp_lt_u32_e64 s[40:41], s40, v120
	s_and_b64 s[96:97], vcc, s[40:41]
	s_andn2_b64 vcc, exec, s[4:5]
	s_waitcnt lgkmcnt(6)
	v_mfma_f32_32x32x16_bf16 v[32:47], v[36:39], v[64:67], 0
	s_waitcnt lgkmcnt(5)
	v_mfma_f32_32x32x16_bf16 v[48:63], v[146:149], v[68:71], v[48:63]
	s_waitcnt lgkmcnt(4)
	v_mfma_f32_32x32x16_bf16 v[32:47], v[150:153], v[68:71], v[32:47]
	s_nop 0
	s_nop 0
	s_waitcnt lgkmcnt(3)
	v_mfma_f32_32x32x16_bf16 v[48:63], v[228:231], v[72:75], v[48:63]
	s_waitcnt lgkmcnt(2)
	v_mfma_f32_32x32x16_bf16 v[32:47], v[232:235], v[72:75], v[32:47]
	s_nop 0
	s_nop 0
	s_waitcnt lgkmcnt(1)
	v_mfma_f32_32x32x16_bf16 v[48:63], v[236:239], v[76:79], v[48:63]
	s_waitcnt lgkmcnt(0)
	v_mfma_f32_32x32x16_bf16 v[32:47], v[240:243], v[76:79], v[32:47]
	s_nop 9
	v_mul_f32_e32 v147, 0x3e000000, v48
	v_cndmask_b32_e64 v48, 0, 1, s[4:5]
	v_cmp_ne_u32_e64 s[40:41], 1, v48
	s_cbranch_vccnz .Lnat_np
	v_lshl_add_u32 v222, v124, 2, s78
	ds_read_b32 v190, v222 offset:16660
	ds_read_b32 v191, v222 offset:16668
	ds_read_b32 v192, v222 offset:16692
	ds_read_b32 v193, v222 offset:16700
	ds_read_b32 v194, v222 offset:16724
	ds_read_b32 v195, v222 offset:16732
	ds_read_b32 v196, v222 offset:16756
	ds_read_b32 v197, v222 offset:16764
	ds_read_b32 v198, v222 offset:16788
	ds_read_b32 v199, v222 offset:16796
	ds_read_b32 v200, v222 offset:16820
	ds_read_b32 v201, v222 offset:16828
	ds_read_b32 v202, v222 offset:16852
	ds_read_b32 v203, v222 offset:16860
	ds_read_b32 v204, v222 offset:16884
	ds_read_b32 v205, v222 offset:16892
	ds_read_b32 v206, v222 offset:16664
	ds_read_b32 v207, v222 offset:16672
	ds_read_b32 v208, v222 offset:16696
	ds_read_b32 v209, v222 offset:16704
	ds_read_b32 v210, v222 offset:16728
	ds_read_b32 v211, v222 offset:16736
	ds_read_b32 v212, v222 offset:16760
	ds_read_b32 v213, v222 offset:16768
	ds_read_b32 v214, v222 offset:16792
	ds_read_b32 v215, v222 offset:16800
	ds_read_b32 v216, v222 offset:16824
	ds_read_b32 v217, v222 offset:16832
	ds_read_b32 v218, v222 offset:16856
	ds_read_b32 v219, v222 offset:16864
	ds_read_b32 v220, v222 offset:16888
	ds_read_b32 v221, v222 offset:16896
	s_waitcnt lgkmcnt(0)
	s_and_b64 vcc, s[96:97], s[64:65]
	v_add_f32_e32 v48, v147, v190
	v_cndmask_b32_e32 v147, v169, v48, vcc
	v_mul_f32_e32 v146, 0x3e000000, v49
	s_and_b64 vcc, s[96:97], s[66:67]
	v_add_f32_e32 v48, v146, v206
	v_cndmask_b32_e32 v146, v169, v48, vcc
	v_mul_f32_e32 v119, 0x3e000000, v50
	s_and_b64 vcc, s[96:97], s[68:69]
	v_add_f32_e32 v48, v119, v191
	v_cndmask_b32_e32 v119, v169, v48, vcc
	v_mul_f32_e32 v145, 0x3e000000, v51
	s_and_b64 vcc, s[96:97], s[70:71]
	v_add_f32_e32 v48, v145, v207
	v_cndmask_b32_e32 v145, v169, v48, vcc
	v_mul_f32_e32 v51, 0x3e000000, v52
	s_and_b64 vcc, s[96:97], s[72:73]
	v_add_f32_e32 v48, v51, v192
	v_cndmask_b32_e32 v51, v169, v48, vcc
	v_mul_f32_e32 v52, 0x3e000000, v53
	s_and_b64 vcc, s[96:97], s[74:75]
	v_add_f32_e32 v48, v52, v208
	v_cndmask_b32_e32 v52, v169, v48, vcc
	v_mul_f32_e32 v48, 0x3e000000, v54
	v_readlane_b32 s4, v254, 45
	v_readlane_b32 s5, v254, 46
	s_and_b64 vcc, s[96:97], s[4:5]
	v_add_f32_e32 v48, v48, v193
	v_cndmask_b32_e32 v48, v169, v48, vcc
	v_mul_f32_e32 v50, 0x3e000000, v55
	v_readlane_b32 s4, v254, 47
	v_readlane_b32 s5, v254, 48
	s_and_b64 vcc, s[96:97], s[4:5]
	v_add_f32_e32 v49, v50, v209
	v_cndmask_b32_e32 v50, v169, v49, vcc
	v_mul_f32_e32 v49, 0x3e000000, v56
	v_readlane_b32 s4, v254, 49
	v_readlane_b32 s5, v254, 50
	v_readlane_b32 vcc_lo, v254, 51
	s_and_b64 s[4:5], s[96:97], s[4:5]
	v_readlane_b32 vcc_hi, v254, 52
	s_and_b64 vcc, s[4:5], vcc
	v_add_f32_e32 v49, v49, v194
	v_cndmask_b32_e32 v49, v169, v49, vcc
	v_mul_f32_e32 v53, 0x3e000000, v57
	v_readlane_b32 s4, v254, 53
	v_readlane_b32 s5, v254, 54
	v_readlane_b32 vcc_lo, v254, 55
	s_and_b64 s[4:5], s[96:97], s[4:5]
	v_readlane_b32 vcc_hi, v254, 56
	s_and_b64 vcc, s[4:5], vcc
	v_add_f32_e32 v53, v53, v210
	v_cndmask_b32_e32 v53, v169, v53, vcc
	v_mul_f32_e32 v54, 0x3e000000, v58
	v_readlane_b32 s4, v254, 57
	v_readlane_b32 s5, v254, 58
	v_readlane_b32 vcc_lo, v255, 26
	s_and_b64 s[4:5], s[96:97], s[4:5]
	v_readlane_b32 vcc_hi, v255, 27
	s_and_b64 vcc, s[4:5], vcc
	v_add_f32_e32 v54, v54, v195
	v_cndmask_b32_e32 v54, v169, v54, vcc
	v_mul_f32_e32 v55, 0x3e000000, v59
	v_readlane_b32 s4, v255, 28
	v_readlane_b32 s5, v255, 29
	v_readlane_b32 vcc_lo, v255, 30
	s_and_b64 s[4:5], s[96:97], s[4:5]
	v_readlane_b32 vcc_hi, v255, 31
	s_and_b64 vcc, s[4:5], vcc
	v_add_f32_e32 v55, v55, v211
	v_cndmask_b32_e32 v55, v169, v55, vcc
	v_mul_f32_e32 v56, 0x3e000000, v60
	v_readlane_b32 s4, v255, 32
	v_readlane_b32 s5, v255, 33
	v_readlane_b32 vcc_lo, v255, 34
	s_and_b64 s[4:5], s[96:97], s[4:5]
	v_readlane_b32 vcc_hi, v255, 35
	s_and_b64 vcc, s[4:5], vcc
	v_add_f32_e32 v56, v56, v196
	v_cndmask_b32_e32 v56, v169, v56, vcc
	v_mul_f32_e32 v57, 0x3e000000, v61
	v_readlane_b32 s4, v255, 36
	v_readlane_b32 s5, v255, 37
	v_readlane_b32 vcc_lo, v255, 38
	s_and_b64 s[4:5], s[96:97], s[4:5]
	v_readlane_b32 vcc_hi, v255, 39
	s_and_b64 vcc, s[4:5], vcc
	v_add_f32_e32 v57, v57, v212
	v_cndmask_b32_e32 v57, v169, v57, vcc
	v_mul_f32_e32 v58, 0x3e000000, v62
	v_readlane_b32 s4, v255, 40
	v_readlane_b32 s5, v255, 41
	v_readlane_b32 vcc_lo, v255, 42
	s_and_b64 s[4:5], s[96:97], s[4:5]
	v_readlane_b32 vcc_hi, v255, 43
	s_and_b64 vcc, s[4:5], vcc
	v_add_f32_e32 v58, v58, v197
	v_cndmask_b32_e32 v58, v169, v58, vcc
	v_mul_f32_e32 v59, 0x3e000000, v63
	v_readlane_b32 s4, v255, 44
	v_readlane_b32 s5, v255, 45
	v_readlane_b32 vcc_lo, v255, 46
	s_and_b64 s[4:5], s[96:97], s[4:5]
	v_readlane_b32 vcc_hi, v255, 47
	s_and_b64 vcc, s[4:5], vcc
	v_add_f32_e32 v59, v59, v213
	v_cndmask_b32_e32 v59, v169, v59, vcc
	v_mul_f32_e32 v60, 0x3e000000, v32
	v_readlane_b32 s4, v255, 48
	v_readlane_b32 s5, v255, 49
	v_readlane_b32 vcc_lo, v255, 50
	s_and_b64 s[4:5], s[96:97], s[4:5]
	v_readlane_b32 vcc_hi, v255, 51
	s_and_b64 vcc, s[4:5], vcc
	v_add_f32_e32 v32, v60, v198
	v_cndmask_b32_e32 v60, v169, v32, vcc
	v_mul_f32_e32 v61, 0x3e000000, v33
	v_readlane_b32 s4, v255, 52
	v_readlane_b32 s5, v255, 53
	v_readlane_b32 vcc_lo, v255, 54
	s_and_b64 s[4:5], s[96:97], s[4:5]
	v_readlane_b32 vcc_hi, v255, 55
	s_and_b64 vcc, s[4:5], vcc
	v_add_f32_e32 v32, v61, v214
	v_cndmask_b32_e32 v61, v169, v32, vcc
	v_mul_f32_e32 v62, 0x3e000000, v34
	v_readlane_b32 s4, v255, 56
	v_readlane_b32 s5, v255, 57
	v_readlane_b32 vcc_lo, v255, 58
	s_and_b64 s[4:5], s[96:97], s[4:5]
	v_readlane_b32 vcc_hi, v255, 59
	s_and_b64 vcc, s[4:5], vcc
	v_add_f32_e32 v32, v62, v199
	v_cndmask_b32_e32 v62, v169, v32, vcc
	v_mul_f32_e32 v150, 0x3e000000, v35
	v_readlane_b32 s4, v255, 60
	v_readlane_b32 s5, v255, 61
	v_readlane_b32 vcc_lo, v255, 62
	s_and_b64 s[4:5], s[96:97], s[4:5]
	v_readlane_b32 vcc_hi, v255, 63
	s_and_b64 vcc, s[4:5], vcc
	v_add_f32_e32 v32, v150, v215
	v_cndmask_b32_e32 v150, v169, v32, vcc
	v_mul_f32_e32 v151, 0x3e000000, v36
	s_and_b64 s[4:5], s[96:97], s[6:7]
	s_and_b64 vcc, s[4:5], s[8:9]
	v_add_f32_e32 v32, v151, v200
	v_cndmask_b32_e32 v151, v169, v32, vcc
	v_mul_f32_e32 v153, 0x3e000000, v37
	s_and_b64 s[4:5], s[96:97], s[10:11]
	s_and_b64 vcc, s[4:5], s[12:13]
	v_add_f32_e32 v32, v153, v216
	v_cndmask_b32_e32 v153, v169, v32, vcc
	v_mul_f32_e32 v149, 0x3e000000, v38
	s_and_b64 s[4:5], s[96:97], s[14:15]
	s_and_b64 vcc, s[4:5], s[16:17]
	v_add_f32_e32 v32, v149, v201
	v_cndmask_b32_e32 v149, v169, v32, vcc
	v_mul_f32_e32 v152, 0x3e000000, v39
	s_and_b64 s[4:5], s[96:97], s[18:19]
	s_and_b64 vcc, s[4:5], s[20:21]
	v_add_f32_e32 v32, v152, v217
	v_cndmask_b32_e32 v152, v169, v32, vcc
	v_mul_f32_e32 v63, 0x3e000000, v40
	s_and_b64 vcc, s[96:97], s[22:23]
	v_add_f32_e32 v32, v63, v202
	v_cndmask_b32_e32 v63, v169, v32, vcc
	v_mul_f32_e32 v148, 0x3e000000, v41
	s_and_b64 vcc, s[96:97], s[24:25]
	v_add_f32_e32 v32, v148, v218
	v_cndmask_b32_e32 v148, v169, v32, vcc
	v_mul_f32_e32 v41, 0x3e000000, v42
	s_and_b64 vcc, s[96:97], s[26:27]
	v_add_f32_e32 v32, v41, v203
	v_cndmask_b32_e32 v41, v169, v32, vcc
	v_mul_f32_e32 v42, 0x3e000000, v43
	s_and_b64 vcc, s[96:97], s[28:29]
	v_add_f32_e32 v32, v42, v219
	v_cndmask_b32_e32 v42, v169, v32, vcc
	v_mul_f32_e32 v39, 0x3e000000, v44
	s_and_b64 vcc, s[96:97], s[30:31]
	v_add_f32_e32 v32, v39, v204
	v_cndmask_b32_e32 v39, v169, v32, vcc
	v_mul_f32_e32 v45, 0x3e000000, v45
	s_and_b64 vcc, s[96:97], s[34:35]
	v_add_f32_e32 v32, v45, v220
	v_cndmask_b32_e32 v45, v169, v32, vcc
	v_mul_f32_e32 v46, 0x3e000000, v46
	s_and_b64 vcc, s[96:97], s[0:1]
	v_add_f32_e32 v32, v46, v205
	v_cndmask_b32_e32 v46, v169, v32, vcc
	v_mul_f32_e32 v154, 0x3e000000, v47
	s_and_b64 vcc, s[96:97], s[38:39]
	v_add_f32_e32 v32, v154, v221
	v_cndmask_b32_e32 v154, v169, v32, vcc
	s_branch .LBB0_334

.LBB0_345:
	global_load_dwordx4 v[80:83], v[80:81], off
	s_nop 0
	global_load_dwordx4 v[84:87], v[84:85], off
	s_nop 0
	global_load_dwordx4 v[104:107], v[108:109], off offset:16
	s_nop 0
	global_load_dwordx4 v[108:111], v[108:109], off
	s_barrier
	ds_write_b128 v125, v[32:35]
	ds_write_b128 v126, v[36:39]
	ds_write_b128 v223, v[40:43] offset:8192
	ds_write_b128 v223, v[44:47] offset:8208
	s_waitcnt lgkmcnt(0)
	s_barrier
	ds_read_b128 v[32:35], v124
	ds_read_b128 v[48:51], v124 offset:4096
	ds_read_b128 v[144:147], v123
	ds_read_b128 v[148:151], v123 offset:4096
	ds_read_b128 v[228:231], v122
	ds_read_b128 v[232:235], v122 offset:4096
	ds_read_b128 v[236:239], v121
	ds_read_b128 v[240:243], v121 offset:4096
	s_waitcnt lgkmcnt(7)
	v_mfma_f32_32x32x16_bf16 v[32:47], v[32:35], v[76:79], 0
	s_add_i32 s4, s12, s13
	s_addk_i32 s4, 0xff80
	s_cmp_gt_i32 s4, -1
	v_cndmask_b32_e64 v134, 0, 1, s[0:1]
	v_add_u32_e32 v143, s13, v138
	s_cselect_b64 s[8:9], -1, 0
	s_waitcnt lgkmcnt(6)
	v_mfma_f32_32x32x16_bf16 v[48:63], v[48:51], v[76:79], 0
	v_cmp_ne_u32_e64 s[4:5], 1, v134
	s_andn2_b64 vcc, exec, s[0:1]
	s_waitcnt lgkmcnt(5)
	v_mfma_f32_32x32x16_bf16 v[32:47], v[144:147], v[72:75], v[32:47]
	s_waitcnt lgkmcnt(4)
	v_mfma_f32_32x32x16_bf16 v[48:63], v[148:151], v[72:75], v[48:63]
	s_nop 0
	s_nop 0
	s_waitcnt lgkmcnt(3)
	v_mfma_f32_32x32x16_bf16 v[32:47], v[228:231], v[68:71], v[32:47]
	s_waitcnt lgkmcnt(2)
	v_mfma_f32_32x32x16_bf16 v[48:63], v[232:235], v[68:71], v[48:63]
	s_nop 0
	s_nop 0
	s_waitcnt lgkmcnt(1)
	v_mfma_f32_32x32x16_bf16 v[32:47], v[236:239], v[64:67], v[32:47]
	v_add_u32_e32 v144, s13, v127
	s_waitcnt lgkmcnt(0)
	v_mfma_f32_32x32x16_bf16 v[48:63], v[240:243], v[64:67], v[48:63]
	s_nop 8
	v_mul_f32_e32 v33, 0x3e000000, v33
	s_cbranch_vccnz .LBB0_379
	v_add_u32_e32 v135, 1, v144
	v_add_u32_e32 v134, 0xffffff81, v143
	v_cmp_gt_u32_e32 vcc, s96, v135
	s_and_b64 s[16:17], s[8:9], vcc
	v_cmp_gt_i32_e32 vcc, s49, v134
	s_and_b64 vcc, s[16:17], vcc
	s_nop 0
	v_cndmask_b32_e32 v33, v169, v33, vcc
	s_and_b64 vcc, exec, s[4:5]
	v_mul_f32_e32 v34, 0x3e000000, v34
	s_cbranch_vccz .LBB0_380

.LBB0_409:
	s_waitcnt vmcnt(0)
	v_cvt_pk_bf16_f32 v32, v108, v109
	v_cvt_pk_bf16_f32 v33, v110, v111
	v_cvt_pk_bf16_f32 v34, v104, v105
	v_cvt_pk_bf16_f32 v35, v106, v107
	v_cvt_pk_bf16_f32 v36, v84, v85
	v_cvt_pk_bf16_f32 v37, v86, v87
	v_cvt_pk_bf16_f32 v38, v80, v81
	v_cvt_pk_bf16_f32 v39, v82, v83
	v_cvt_pk_bf16_f32 v40, v100, v101
	v_cvt_pk_bf16_f32 v41, v102, v103
	v_cvt_pk_bf16_f32 v42, v96, v97
	v_cvt_pk_bf16_f32 v43, v98, v99
	v_cvt_pk_bf16_f32 v44, v92, v93
	v_cvt_pk_bf16_f32 v45, v94, v95
	v_cvt_pk_bf16_f32 v46, v88, v89
	v_cvt_pk_bf16_f32 v47, v90, v91
	s_barrier
	ds_write_b128 v125, v[32:35]
	ds_write_b128 v126, v[36:39]
	ds_write_b128 v223, v[40:43] offset:8192
	ds_write_b128 v223, v[44:47] offset:8208
	s_waitcnt lgkmcnt(0)
	s_barrier
	ds_read_b128 v[32:35], v124
	ds_read_b128 v[48:51], v124 offset:4096
	ds_read_b128 v[228:231], v123
	ds_read_b128 v[80:83], v123 offset:4096
	ds_read_b128 v[232:235], v122
	ds_read_b128 v[236:239], v122 offset:4096
	ds_read_b128 v[240:243], v121 offset:4096
	ds_read_b128 v[244:247], v121
	s_waitcnt lgkmcnt(7)
	v_mfma_f32_32x32x16_bf16 v[32:47], v[32:35], v[76:79], 0
	s_mov_b32 s0, 0x3e000000
	s_lshl_b32 s92, s10, 1
	v_lshlrev_b32_e32 v128, 1, v117
	s_waitcnt lgkmcnt(6)
	v_mfma_f32_32x32x16_bf16 v[48:63], v[48:51], v[76:79], 0
	s_waitcnt lgkmcnt(5)
	v_mfma_f32_32x32x16_bf16 v[32:47], v[228:231], v[72:75], v[32:47]
	s_waitcnt lgkmcnt(4)
	v_mfma_f32_32x32x16_bf16 v[48:63], v[80:83], v[72:75], v[48:63]
	s_nop 0
	s_nop 0
	s_waitcnt lgkmcnt(3)
	v_mfma_f32_32x32x16_bf16 v[32:47], v[232:235], v[68:71], v[32:47]
	s_waitcnt lgkmcnt(2)
	v_mfma_f32_32x32x16_bf16 v[48:63], v[236:239], v[68:71], v[48:63]
	s_nop 0
	s_nop 0
	s_waitcnt lgkmcnt(1)
	v_mfma_f32_32x32x16_bf16 v[48:63], v[240:243], v[64:67], v[48:63]
	s_waitcnt lgkmcnt(0)
	v_mfma_f32_32x32x16_bf16 v[32:47], v[244:247], v[64:67], v[32:47]
	s_nop 9
	v_mul_f32_e64 v62, v62, s0
	v_mul_f32_e64 v63, v63, s0
	v_mul_f32_e64 v60, v60, s0
	v_mul_f32_e64 v61, v61, s0
	v_mul_f32_e64 v58, v58, s0
	v_mul_f32_e64 v59, v59, s0
	v_pk_mul_f32 v[56:57], v[56:57], s[0:1] op_sel_hi:[1,0]
	v_pk_mul_f32 v[54:55], v[54:55], s[0:1] op_sel_hi:[1,0]
	v_pk_mul_f32 v[52:53], v[52:53], s[0:1] op_sel_hi:[1,0]
	v_pk_mul_f32 v[50:51], v[50:51], s[0:1] op_sel_hi:[1,0]
	v_pk_mul_f32 v[48:49], v[48:49], s[0:1] op_sel_hi:[1,0]
	v_pk_mul_f32 v[46:47], v[46:47], s[0:1] op_sel_hi:[1,0]
	v_pk_mul_f32 v[44:45], v[44:45], s[0:1] op_sel_hi:[1,0]
	v_pk_mul_f32 v[42:43], v[42:43], s[0:1] op_sel_hi:[1,0]
	v_pk_mul_f32 v[40:41], v[40:41], s[0:1] op_sel_hi:[1,0]
	v_pk_mul_f32 v[38:39], v[38:39], s[0:1] op_sel_hi:[1,0]
	v_pk_mul_f32 v[36:37], v[36:37], s[0:1] op_sel_hi:[1,0]
	v_pk_mul_f32 v[34:35], v[34:35], s[0:1] op_sel_hi:[1,0]
	v_pk_mul_f32 v[32:33], v[32:33], s[0:1] op_sel_hi:[1,0]
	s_mov_b32 s0, 0xf149f2ca
	v_max3_f32 v64, v32, s0, v33
	v_max3_f32 v64, v64, v34, v35
	v_max3_f32 v64, v64, v36, v37
	v_max3_f32 v64, v64, v38, v39
	v_max3_f32 v64, v64, v40, v41
	v_max3_f32 v64, v64, v42, v43
	v_max3_f32 v64, v64, v44, v45
	v_max3_f32 v64, v64, v46, v47
	v_max3_f32 v64, v64, v48, v49
	v_max3_f32 v64, v64, v50, v51
	v_max3_f32 v64, v64, v52, v53
	v_max3_f32 v64, v64, v54, v55
	v_max3_f32 v64, v64, v56, v57
	v_max3_f32 v64, v64, v58, v59
	v_max3_f32 v64, v64, v60, v61
	v_max3_f32 v64, v64, v62, v63
	ds_bpermute_b32 v65, v118, v64
	v_cmp_lt_f32_e32 vcc, s86, v33
	s_waitcnt lgkmcnt(0)
	v_max3_f32 v64, v144, v64, v65
	v_sub_f32_e32 v67, v33, v64
	v_sub_f32_e32 v66, v32, v64
	v_mul_f32_e32 v67, 0x3fb8aa3b, v67
	v_exp_f32_e32 v67, v67
	v_mul_f32_e32 v66, 0x3fb8aa3b, v66
	v_sub_f32_e32 v68, v35, v64
	v_exp_f32_e32 v66, v66
	v_sub_f32_e32 v33, v34, v64
	v_mul_f32_e32 v68, 0x3fb8aa3b, v68
	v_exp_f32_e32 v68, v68
	v_mul_f32_e32 v33, 0x3fb8aa3b, v33
	v_exp_f32_e32 v33, v33
	v_cndmask_b32_e32 v67, 0, v67, vcc
	v_cmp_lt_f32_e32 vcc, s86, v32
	v_sub_f32_e32 v65, v144, v64
	v_mul_f32_e32 v65, 0x3fb8aa3b, v65
	v_cndmask_b32_e32 v66, 0, v66, vcc
	v_cmp_lt_f32_e32 vcc, s86, v35
	v_add_f32_e32 v32, 0, v66
	v_add_f32_e32 v32, v67, v32
	v_cndmask_b32_e32 v68, 0, v68, vcc
	v_cmp_lt_f32_e32 vcc, s86, v34
	v_sub_f32_e32 v34, v37, v64
	v_mul_f32_e32 v34, 0x3fb8aa3b, v34
	v_cndmask_b32_e32 v69, 0, v33, vcc
	v_sub_f32_e32 v33, v36, v64
	v_exp_f32_e32 v34, v34
	v_mul_f32_e32 v33, 0x3fb8aa3b, v33
	v_exp_f32_e32 v33, v33
	v_cmp_lt_f32_e32 vcc, s86, v37
	v_add_f32_e32 v32, v69, v32
	v_add_f32_e32 v32, v68, v32
	v_cndmask_b32_e32 v70, 0, v34, vcc
	v_cmp_lt_f32_e32 vcc, s86, v36
	v_sub_f32_e32 v34, v39, v64
	v_mul_f32_e32 v34, 0x3fb8aa3b, v34
	v_cndmask_b32_e32 v71, 0, v33, vcc
	v_sub_f32_e32 v33, v38, v64
	v_exp_f32_e32 v34, v34
	v_mul_f32_e32 v33, 0x3fb8aa3b, v33
	v_exp_f32_e32 v33, v33
	v_cmp_lt_f32_e32 vcc, s86, v39
	v_add_f32_e32 v32, v71, v32
	v_add_f32_e32 v32, v70, v32
	v_cndmask_b32_e32 v39, 0, v34, vcc
	v_cmp_lt_f32_e32 vcc, s86, v38
	v_sub_f32_e32 v34, v41, v64
	v_mul_f32_e32 v34, 0x3fb8aa3b, v34
	v_cndmask_b32_e32 v72, 0, v33, vcc
	v_sub_f32_e32 v33, v40, v64
	v_exp_f32_e32 v34, v34
	v_mul_f32_e32 v33, 0x3fb8aa3b, v33
	v_exp_f32_e32 v33, v33
	v_cmp_lt_f32_e32 vcc, s86, v41
	v_add_f32_e32 v32, v72, v32
	v_add_f32_e32 v32, v39, v32
	v_cndmask_b32_e32 v73, 0, v34, vcc
	v_cmp_lt_f32_e32 vcc, s86, v40
	v_sub_f32_e32 v34, v43, v64
	v_mul_f32_e32 v34, 0x3fb8aa3b, v34
	v_cndmask_b32_e32 v74, 0, v33, vcc
	v_sub_f32_e32 v33, v42, v64
	v_exp_f32_e32 v34, v34
	v_mul_f32_e32 v33, 0x3fb8aa3b, v33
	v_exp_f32_e32 v33, v33
	v_cmp_lt_f32_e32 vcc, s86, v43
	v_add_f32_e32 v32, v74, v32
	v_add_f32_e32 v32, v73, v32
	v_cndmask_b32_e32 v75, 0, v34, vcc
	v_cmp_lt_f32_e32 vcc, s86, v42
	v_sub_f32_e32 v34, v45, v64
	v_mul_f32_e32 v34, 0x3fb8aa3b, v34
	v_cndmask_b32_e32 v76, 0, v33, vcc
	v_sub_f32_e32 v33, v44, v64
	v_exp_f32_e32 v34, v34
	v_mul_f32_e32 v33, 0x3fb8aa3b, v33
	v_exp_f32_e32 v33, v33
	v_cmp_lt_f32_e32 vcc, s86, v45
	v_add_f32_e32 v32, v76, v32
	v_add_f32_e32 v32, v75, v32
	v_cndmask_b32_e32 v45, 0, v34, vcc
	v_cmp_lt_f32_e32 vcc, s86, v44
	v_sub_f32_e32 v34, v47, v64
	v_mul_f32_e32 v34, 0x3fb8aa3b, v34
	v_cndmask_b32_e32 v77, 0, v33, vcc
	v_sub_f32_e32 v33, v46, v64
	v_exp_f32_e32 v34, v34
	v_mul_f32_e32 v33, 0x3fb8aa3b, v33
	v_exp_f32_e32 v33, v33
	v_cmp_lt_f32_e32 vcc, s86, v47
	v_add_f32_e32 v32, v77, v32
	v_add_f32_e32 v32, v45, v32
	v_cndmask_b32_e32 v47, 0, v34, vcc
	v_cmp_lt_f32_e32 vcc, s86, v46
	v_sub_f32_e32 v34, v49, v64
	v_mul_f32_e32 v34, 0x3fb8aa3b, v34
	v_cndmask_b32_e32 v46, 0, v33, vcc
	v_sub_f32_e32 v33, v48, v64
	v_exp_f32_e32 v34, v34
	v_mul_f32_e32 v33, 0x3fb8aa3b, v33
	v_exp_f32_e32 v33, v33
	v_cmp_lt_f32_e32 vcc, s86, v49
	v_add_f32_e32 v32, v46, v32
	v_add_f32_e32 v32, v47, v32
	v_cndmask_b32_e32 v49, 0, v34, vcc
	v_cmp_lt_f32_e32 vcc, s86, v48
	v_sub_f32_e32 v34, v51, v64
	v_mul_f32_e32 v34, 0x3fb8aa3b, v34
	v_cndmask_b32_e32 v48, 0, v33, vcc
	v_sub_f32_e32 v33, v50, v64
	v_exp_f32_e32 v34, v34
	v_mul_f32_e32 v33, 0x3fb8aa3b, v33
	v_exp_f32_e32 v33, v33
	v_cmp_lt_f32_e32 vcc, s86, v51
	v_add_f32_e32 v32, v48, v32
	v_add_f32_e32 v32, v49, v32
	v_cndmask_b32_e32 v51, 0, v34, vcc
	v_cmp_lt_f32_e32 vcc, s86, v50
	v_sub_f32_e32 v34, v53, v64
	v_mul_f32_e32 v34, 0x3fb8aa3b, v34
	v_cndmask_b32_e32 v50, 0, v33, vcc
	v_sub_f32_e32 v33, v52, v64
	v_exp_f32_e32 v34, v34
	v_mul_f32_e32 v33, 0x3fb8aa3b, v33
	v_exp_f32_e32 v33, v33
	v_cmp_lt_f32_e32 vcc, s86, v53
	v_add_f32_e32 v32, v50, v32
	v_add_f32_e32 v32, v51, v32
	v_cndmask_b32_e32 v53, 0, v34, vcc
	v_cmp_lt_f32_e32 vcc, s86, v52
	v_sub_f32_e32 v34, v55, v64
	v_mul_f32_e32 v34, 0x3fb8aa3b, v34
	v_cndmask_b32_e32 v52, 0, v33, vcc
	v_sub_f32_e32 v33, v54, v64
	v_exp_f32_e32 v34, v34
	v_mul_f32_e32 v33, 0x3fb8aa3b, v33
	v_exp_f32_e32 v33, v33
	v_cmp_lt_f32_e32 vcc, s86, v55
	v_add_f32_e32 v32, v52, v32
	v_add_f32_e32 v32, v53, v32
	v_cndmask_b32_e32 v55, 0, v34, vcc
	v_cmp_lt_f32_e32 vcc, s86, v54
	v_sub_f32_e32 v34, v57, v64
	v_mul_f32_e32 v34, 0x3fb8aa3b, v34
	v_cndmask_b32_e32 v54, 0, v33, vcc
	v_sub_f32_e32 v33, v56, v64
	v_exp_f32_e32 v34, v34
	v_mul_f32_e32 v33, 0x3fb8aa3b, v33
	v_exp_f32_e32 v33, v33
	v_cmp_lt_f32_e32 vcc, s86, v57
	v_add_f32_e32 v32, v54, v32
	v_add_f32_e32 v32, v55, v32
	v_cndmask_b32_e32 v57, 0, v34, vcc
	v_cmp_lt_f32_e32 vcc, s86, v56
	v_sub_f32_e32 v34, v59, v64
	v_mul_f32_e32 v34, 0x3fb8aa3b, v34
	v_cndmask_b32_e32 v56, 0, v33, vcc
	v_sub_f32_e32 v33, v58, v64
	v_exp_f32_e32 v34, v34
	v_mul_f32_e32 v33, 0x3fb8aa3b, v33
	v_exp_f32_e32 v33, v33
	v_cmp_lt_f32_e32 vcc, s86, v59
	v_add_f32_e32 v32, v56, v32
	v_add_f32_e32 v32, v57, v32
	v_cndmask_b32_e32 v59, 0, v34, vcc
	v_cmp_lt_f32_e32 vcc, s86, v58
	v_sub_f32_e32 v34, v61, v64
	v_mul_f32_e32 v34, 0x3fb8aa3b, v34
	v_cndmask_b32_e32 v58, 0, v33, vcc
	v_sub_f32_e32 v33, v60, v64
	v_exp_f32_e32 v34, v34
	v_mul_f32_e32 v33, 0x3fb8aa3b, v33
	v_exp_f32_e32 v33, v33
	v_cmp_lt_f32_e32 vcc, s86, v61
	v_add_f32_e32 v32, v58, v32
	v_add_f32_e32 v32, v59, v32
	v_cndmask_b32_e32 v61, 0, v34, vcc
	v_cmp_lt_f32_e32 vcc, s86, v60
	v_exp_f32_e32 v44, v65
	ds_read_b64_tr_b16 v[40:41], v225 offset:8192
	ds_read_b64_tr_b16 v[42:43], v225 offset:9216
	v_cndmask_b32_e32 v60, 0, v33, vcc
	v_add_f32_e32 v65, v60, v32
	ds_read_b64_tr_b16 v[32:33], v224 offset:8192
	ds_read_b64_tr_b16 v[34:35], v224 offset:9216
	v_pk_mul_f32 v[30:31], v[30:31], v[44:45] op_sel_hi:[1,0]
	v_pk_mul_f32 v[28:29], v[28:29], v[44:45] op_sel_hi:[1,0]
	v_pk_mul_f32 v[26:27], v[26:27], v[44:45] op_sel_hi:[1,0]
	v_pk_mul_f32 v[24:25], v[24:25], v[44:45] op_sel_hi:[1,0]
	v_pk_mul_f32 v[22:23], v[22:23], v[44:45] op_sel_hi:[1,0]
	v_pk_mul_f32 v[20:21], v[20:21], v[44:45] op_sel_hi:[1,0]
	v_pk_mul_f32 v[18:19], v[18:19], v[44:45] op_sel_hi:[1,0]
	v_pk_mul_f32 v[16:17], v[16:17], v[44:45] op_sel_hi:[1,0]
	v_cvt_pk_bf16_f32 v36, v66, v67
	v_cvt_pk_bf16_f32 v37, v69, v68
	v_cvt_pk_bf16_f32 v38, v71, v70
	v_cvt_pk_bf16_f32 v39, v72, v39
	v_pk_mul_f32 v[14:15], v[14:15], v[44:45] op_sel_hi:[1,0]
	v_pk_mul_f32 v[12:13], v[12:13], v[44:45] op_sel_hi:[1,0]
	s_waitcnt lgkmcnt(0)
	v_mfma_f32_32x32x16_bf16 v[16:31], v[32:35], v[36:39], v[16:31]
	ds_read_b64_tr_b16 v[32:33], v224 offset:10240
	ds_read_b64_tr_b16 v[34:35], v224 offset:11264
	v_mul_f32_e64 v10, v10, v44
	v_mul_f32_e64 v11, v11, v44
	v_mul_f32_e64 v8, v8, v44
	v_mul_f32_e64 v9, v9, v44
	v_pk_mul_f32 v[6:7], v[6:7], v[44:45] op_sel_hi:[1,0]
	v_pk_mul_f32 v[4:5], v[4:5], v[44:45] op_sel_hi:[1,0]
	v_pk_mul_f32 v[2:3], v[2:3], v[44:45] op_sel_hi:[1,0]
	v_pk_mul_f32 v[0:1], v[0:1], v[44:45] op_sel_hi:[1,0]
	v_sub_f32_e32 v66, v62, v64
	v_cmp_lt_f32_e32 vcc, s86, v63
	v_mfma_f32_32x32x16_bf16 v[0:15], v[40:43], v[36:39], v[0:15]
	ds_read_b64_tr_b16 v[40:41], v225 offset:10240
	ds_read_b64_tr_b16 v[42:43], v225 offset:11264
	v_cvt_pk_bf16_f32 v36, v74, v73
	v_cvt_pk_bf16_f32 v37, v76, v75
	v_cvt_pk_bf16_f32 v38, v77, v45
	v_cvt_pk_bf16_f32 v39, v46, v47
	v_add_f32_e32 v65, v61, v65
	s_waitcnt lgkmcnt(2)
	v_mfma_f32_32x32x16_bf16 v[16:31], v[32:35], v[36:39], v[16:31]
	v_sub_f32_e32 v32, v63, v64
	v_mul_f32_e32 v32, 0x3fb8aa3b, v32
	v_exp_f32_e32 v32, v32
	v_mul_f32_e32 v33, 0x3fb8aa3b, v66
	v_exp_f32_e32 v45, v33
	v_cndmask_b32_e32 v46, 0, v32, vcc
	s_waitcnt lgkmcnt(0)
	v_mfma_f32_32x32x16_bf16 v[0:15], v[40:43], v[36:39], v[0:15]
	ds_read_b64_tr_b16 v[32:33], v224 offset:12288
	ds_read_b64_tr_b16 v[34:35], v224 offset:13312
	ds_read_b64_tr_b16 v[40:41], v225 offset:12288
	ds_read_b64_tr_b16 v[42:43], v225 offset:13312
	v_cmp_lt_f32_e32 vcc, s86, v62
	v_cvt_pk_bf16_f32 v36, v48, v49
	v_cvt_pk_bf16_f32 v37, v50, v51
	v_cndmask_b32_e32 v45, 0, v45, vcc
	v_add_f32_e32 v47, v45, v65
	v_cvt_pk_bf16_f32 v38, v52, v53
	v_cvt_pk_bf16_f32 v39, v54, v55
	s_waitcnt lgkmcnt(2)
	s_nop 0
	v_mfma_f32_32x32x16_bf16 v[16:31], v[32:35], v[36:39], v[16:31]
	v_add_f32_e32 v32, v46, v47
	ds_bpermute_b32 v33, v118, v32
	v_cvt_pk_bf16_f32 v35, v45, v46
	v_cvt_pk_bf16_f32 v34, v60, v61
	s_waitcnt lgkmcnt(0)
	v_add_f32_e32 v47, v32, v33
	v_mfma_f32_32x32x16_bf16 v[0:15], v[40:43], v[36:39], v[0:15]
	ds_read_b64_tr_b16 v[36:37], v224 offset:14336
	ds_read_b64_tr_b16 v[38:39], v224 offset:15360
	v_max_f32_e32 v40, v116, v116
	v_max_f32_e32 v40, v64, v40
	v_sub_f32_e32 v41, v64, v40
	v_sub_f32_e32 v40, v116, v40
	v_mul_f32_e32 v41, 0x3fb8aa3b, v41
	v_mul_f32_e32 v40, 0x3fb8aa3b, v40
	v_exp_f32_e32 v45, v41
	v_exp_f32_e32 v46, v40
	ds_read_b64_tr_b16 v[40:41], v225 offset:14336
	ds_read_b64_tr_b16 v[42:43], v225 offset:15360
	v_fmac_f32_e32 v47, v145, v44
	v_cvt_pk_bf16_f32 v32, v56, v57
	v_cvt_pk_bf16_f32 v33, v58, v59
	v_fmac_f32_e32 v46, v45, v47
	s_waitcnt lgkmcnt(2)
	v_mfma_f32_32x32x16_bf16 v[16:31], v[36:39], v[32:35], v[16:31]
	v_div_scale_f32 v36, s[0:1], v46, v46, v45
	v_rcp_f32_e32 v37, v36
	v_readlane_b32 s0, v254, 43
	v_readlane_b32 s1, v254, 44
	s_waitcnt lgkmcnt(0)
	v_mfma_f32_32x32x16_bf16 v[0:15], v[40:43], v[32:35], v[0:15]
	v_fma_f32 v32, -v36, v37, 1.0
	v_fmac_f32_e32 v37, v32, v37
	v_div_scale_f32 v32, vcc, v45, v46, v45
	v_mul_f32_e32 v33, v32, v37
	v_fma_f32 v34, -v36, v33, v32
	v_fmac_f32_e32 v33, v34, v37
	v_fma_f32 v32, -v36, v33, v32
	v_div_fmas_f32 v32, v32, v37, v33
	v_lshlrev_b64 v[34:35], 11, v[112:113]
	v_div_fixup_f32 v32, v32, v46, v45
	v_lshl_add_u64 v[34:35], s[0:1], 0, v[34:35]
	v_lshl_add_u64 v[34:35], v[34:35], 0, s[92:93]
	v_pk_mul_f32 v[16:17], v[16:17], v[32:33] op_sel_hi:[1,0]
	v_pk_mul_f32 v[18:19], v[18:19], v[32:33] op_sel_hi:[1,0]
	v_cvt_pk_bf16_f32 v16, v16, v17
	v_cvt_pk_bf16_f32 v17, v18, v19
	v_lshl_add_u64 v[18:19], v[34:35], 0, v[128:129]
	s_mov_b64 s[0:1], 0x153ca600
	v_lshl_add_u64 v[34:35], v[18:19], 0, s[0:1]
	s_mov_b32 s0, 0x153ca000
	v_add_co_u32_e32 v18, vcc, s0, v18
	v_pk_mul_f32 v[0:1], v[0:1], v[32:33] op_sel_hi:[1,0]
	v_pk_mul_f32 v[2:3], v[2:3], v[32:33] op_sel_hi:[1,0]
	v_addc_co_u32_e32 v19, vcc, 0, v19, vcc
	v_cvt_pk_bf16_f32 v0, v0, v1
	v_cvt_pk_bf16_f32 v1, v2, v3
	global_store_dwordx2 v[18:19], v[16:17], off offset:1536
	v_pk_mul_f32 v[16:17], v[20:21], v[32:33] op_sel_hi:[1,0]
	v_pk_mul_f32 v[18:19], v[22:23], v[32:33] op_sel_hi:[1,0]
	global_store_dwordx2 v[34:35], v[0:1], off offset:64
	v_pk_mul_f32 v[0:1], v[4:5], v[32:33] op_sel_hi:[1,0]
	v_pk_mul_f32 v[2:3], v[6:7], v[32:33] op_sel_hi:[1,0]
	v_cvt_pk_bf16_f32 v16, v16, v17
	v_cvt_pk_bf16_f32 v17, v18, v19
	v_cvt_pk_bf16_f32 v0, v0, v1
	v_cvt_pk_bf16_f32 v1, v2, v3
	global_store_dwordx2 v[34:35], v[16:17], off offset:16
	v_pk_mul_f32 v[16:17], v[24:25], v[32:33] op_sel_hi:[1,0]
	v_pk_mul_f32 v[18:19], v[26:27], v[32:33] op_sel_hi:[1,0]
	global_store_dwordx2 v[34:35], v[0:1], off offset:80
	v_pk_mul_f32 v[0:1], v[8:9], v[32:33] op_sel_hi:[1,0]
	v_pk_mul_f32 v[2:3], v[10:11], v[32:33] op_sel_hi:[1,0]
	v_cvt_pk_bf16_f32 v16, v16, v17
	v_cvt_pk_bf16_f32 v17, v18, v19
	v_cvt_pk_bf16_f32 v0, v0, v1
	v_cvt_pk_bf16_f32 v1, v2, v3
	global_store_dwordx2 v[34:35], v[16:17], off offset:32
	v_pk_mul_f32 v[16:17], v[28:29], v[32:33] op_sel_hi:[1,0]
	v_pk_mul_f32 v[18:19], v[30:31], v[32:33] op_sel_hi:[1,0]
	global_store_dwordx2 v[34:35], v[0:1], off offset:96
	v_pk_mul_f32 v[0:1], v[12:13], v[32:33] op_sel_hi:[1,0]
	v_pk_mul_f32 v[2:3], v[14:15], v[32:33] op_sel_hi:[1,0]
	v_cvt_pk_bf16_f32 v16, v16, v17
	v_cvt_pk_bf16_f32 v17, v18, v19
	v_cvt_pk_bf16_f32 v0, v0, v1
	v_cvt_pk_bf16_f32 v1, v2, v3
	global_store_dwordx2 v[34:35], v[16:17], off offset:48
	global_store_dwordx2 v[34:35], v[0:1], off offset:112
	s_barrier
